# speedup vs baseline: 1.0241x; 1.0014x over previous
; template <int EPI, int PN>
; __device__ void gemm_phase(const Params& p, const u16* __restrict__ A, const u16* __restrict__ Bt, int nNt, char* smem) {
;     ...
;     for (int kt = 0; kt < 32; ++kt) {
;       asm volatile("s_waitcnt vmcnt(0)" ::: "memory");
;       __builtin_amdgcn_s_barrier();
;       const u16* Ab = ring + (kt & 1) * STG;
;       const u16* Bb = Ab + 16384;
;       u16* st = ring + ((kt + 1) & 1) * STG;
;       const bool pre = (kt + 1 < 32);
;       s16x8 af[2][4], bf[2][2];
;       auto ldfrag = [&](int ks, int slot) {
; #pragma unroll
;         for (int i = 0; i < 4; ++i) {
;           const int row = wr * 128 + i * 32 + lr;
;           af[slot][i] = *(const s16x8*)(Ab + row * 64 + (((ks * 2 + lh) ^ ((row >> 1) & 7)) * 8));
;         }
; #pragma unroll
;         for (int j = 0; j < 2; ++j) {
;           const int rowb = nh * 128 + wc * 64 + j * 32 + lr;
;           bf[slot][j] = *(const s16x8*)(Bb + rowb * 64 + (((ks * 2 + lh) ^ ((rowb >> 1) & 7)) * 8));
;         }
;       };
;       ldfrag(0, 0);
;       ldfrag(1, 1);
;       __builtin_amdgcn_sched_barrier(0);
; #pragma unroll
;       for (int ks = 0; ks < 4; ++ks) {
;         const int slot = ks & 1;
; #pragma unroll
;         for (int i = 0; i < 4; ++i) {
;           acc[i][0] = mfma32(af[slot][i], bf[slot][0], acc[i][0]);
;           acc[i][1] = mfma32(af[slot][i], bf[slot][1], acc[i][1]);
;           __builtin_amdgcn_sched_barrier(0);
;           if (pre && (i & 1) == 0) {
;             const int pi = ks * 2 + (i >> 1);
;             if (pi < 4) glds16(Ag0 + (size_t)pi * 64 * LDK + (kt + 1) * 64, st + (srow + 64 * pi) * 64 + sch * 8);
;             else glds16(Bg0 + (size_t)(pi - 4) * 64 * LDK + (kt + 1) * 64, st + 16384 + (srow + 64 * (pi - 4)) * 64 + sch * 8);
;             __builtin_amdgcn_sched_barrier(0);
;           }
;         }
;         if (ks + 2 < 4) { ldfrag(ks + 2, slot); __builtin_amdgcn_sched_barrier(0); }
;       }
.Lrot129_loop:
	s_add_i32 s13, s12, 0xffff8000
	s_and_b32 s13, s13, 0x8000
	s_lshl_b32 s13, s13, 1
	v_lshl_or_b32 v128, v143, 1, s13
	v_lshl_add_u32 v149, v147, 1, s13
	s_and_b32 s98, s12, 0x8000
	s_lshl_b32 s98, s98, 1
	s_waitcnt lgkmcnt(7)
	v_mfma_f32_32x32x16_bf16 v[64:79], v[178:181], v[194:197], v[64:79]
	v_add3_u32 v226, s98, v162, v156
	s_waitcnt lgkmcnt(6)
	v_mfma_f32_32x32x16_bf16 v[112:127], v[178:181], v[198:201], v[112:127]
	v_readfirstlane_b32 s100, v226
	s_mov_b32 s20, m0
	s_add_i32 m0, s100, 0x8000
	s_nop 0
	global_load_lds_dwordx4 v[160:161], off
	v_mfma_f32_32x32x16_bf16 v[32:47], v[182:185], v[194:197], v[32:47]
	v_lshl_add_u64 v[178:179], v[160:161], 0, s[2:3]
	s_add_i32 m0, s100, 0xa000
	s_nop 0
	global_load_lds_dwordx4 v[178:179], off
	v_mfma_f32_32x32x16_bf16 v[96:111], v[182:185], v[198:201], v[96:111]
	v_lshl_add_u64 v[180:181], v[160:161], 0, s[4:5]
	s_add_i32 m0, s100, 0xc000
	s_nop 0
	global_load_lds_dwordx4 v[180:181], off
	v_mfma_f32_32x32x16_bf16 v[16:31], v[186:189], v[194:197], v[16:31]
	v_lshl_add_u64 v[178:179], v[160:161], 0, s[6:7]
	s_add_i32 m0, s100, 0xe000
	s_nop 0
	global_load_lds_dwordx4 v[178:179], off
	s_mov_b32 m0, s20
	v_mfma_f32_32x32x16_bf16 v[80:95], v[186:189], v[198:201], v[80:95]
	v_mfma_f32_32x32x16_bf16 v[0:15], v[190:193], v[194:197], v[0:15]
	v_mfma_f32_32x32x16_bf16 v[48:63], v[190:193], v[198:201], v[48:63]
	v_lshl_add_u64 v[160:161], v[160:161], 0, s[8:9]
	v_add_u32_e32 v177, v128, v175
	ds_read_b128 v[178:181], v177
	ds_read_b128 v[182:185], v177 offset:4096
	ds_read_b128 v[186:189], v177 offset:8192
	ds_read_b128 v[190:193], v177 offset:12288
	v_add_u32_e32 v177, v149, v175
	ds_read_b128 v[194:197], v177 offset:32768
	ds_read_b128 v[198:201], v177 offset:36864
	s_waitcnt lgkmcnt(7)
	v_mfma_f32_32x32x16_bf16 v[64:79], v[202:205], v[218:221], v[64:79]
	s_waitcnt lgkmcnt(6)
	v_mfma_f32_32x32x16_bf16 v[112:127], v[202:205], v[222:225], v[112:127]
	v_mfma_f32_32x32x16_bf16 v[32:47], v[206:209], v[218:221], v[32:47]
	v_mfma_f32_32x32x16_bf16 v[96:111], v[206:209], v[222:225], v[96:111]
	v_mfma_f32_32x32x16_bf16 v[16:31], v[210:213], v[218:221], v[16:31]
	v_mfma_f32_32x32x16_bf16 v[80:95], v[210:213], v[222:225], v[80:95]
	v_mfma_f32_32x32x16_bf16 v[0:15], v[214:217], v[218:221], v[0:15]
	v_mfma_f32_32x32x16_bf16 v[48:63], v[214:217], v[222:225], v[48:63]
	v_add_u32_e32 v128, v128, v176
	ds_read_b128 v[202:205], v128
	ds_read_b128 v[206:209], v128 offset:4096
	ds_read_b128 v[210:213], v128 offset:8192
	ds_read_b128 v[214:217], v128 offset:12288
	v_add_u32_e32 v128, v149, v176
	ds_read_b128 v[218:221], v128 offset:32768
	ds_read_b128 v[222:225], v128 offset:36864
	s_waitcnt lgkmcnt(7)
	v_mfma_f32_32x32x16_bf16 v[64:79], v[178:181], v[194:197], v[64:79]
	s_waitcnt lgkmcnt(6)
	v_mfma_f32_32x32x16_bf16 v[112:127], v[178:181], v[198:201], v[112:127]
	v_mfma_f32_32x32x16_bf16 v[32:47], v[182:185], v[194:197], v[32:47]
	v_mfma_f32_32x32x16_bf16 v[96:111], v[182:185], v[198:201], v[96:111]
	v_mfma_f32_32x32x16_bf16 v[16:31], v[186:189], v[194:197], v[16:31]
	v_mfma_f32_32x32x16_bf16 v[80:95], v[186:189], v[198:201], v[80:95]
	v_mfma_f32_32x32x16_bf16 v[0:15], v[190:193], v[194:197], v[0:15]
	v_mfma_f32_32x32x16_bf16 v[48:63], v[190:193], v[198:201], v[48:63]
	s_waitcnt vmcnt(0) lgkmcnt(0)
	s_barrier
	v_lshl_or_b32 v227, v143, 1, s98
	v_lshl_add_u32 v229, v147, 1, s98
	v_add_u32_e32 v228, v227, v173
	v_add_u32_e32 v230, v229, v173
	ds_read_b128 v[178:181], v228
	ds_read_b128 v[182:185], v228 offset:4096
	ds_read_b128 v[186:189], v228 offset:8192
	ds_read_b128 v[190:193], v228 offset:12288
	ds_read_b128 v[194:197], v230 offset:32768
	ds_read_b128 v[198:201], v230 offset:36864
	v_add3_u32 v226, s13, v162, v156
	v_mfma_f32_32x32x16_bf16 v[64:79], v[202:205], v[218:221], v[64:79]
	v_readfirstlane_b32 s99, v226
	s_mov_b32 s20, m0
	s_mov_b32 m0, s99
	s_nop 0
	global_load_lds_dwordx4 v[158:159], off
	v_mfma_f32_32x32x16_bf16 v[112:127], v[202:205], v[222:225], v[112:127]
	v_lshl_add_u64 v[232:233], v[158:159], 0, s[2:3]
	s_add_i32 m0, s99, 0x2000
	s_nop 0
	global_load_lds_dwordx4 v[232:233], off
	v_mfma_f32_32x32x16_bf16 v[32:47], v[206:209], v[218:221], v[32:47]
	v_lshl_add_u64 v[234:235], v[158:159], 0, s[4:5]
	s_add_i32 m0, s99, 0x4000
	s_nop 0
	global_load_lds_dwordx4 v[234:235], off
	v_mfma_f32_32x32x16_bf16 v[96:111], v[206:209], v[222:225], v[96:111]
	v_lshl_add_u64 v[232:233], v[158:159], 0, s[6:7]
	s_add_i32 m0, s99, 0x6000
	s_nop 0
	global_load_lds_dwordx4 v[232:233], off
	s_mov_b32 m0, s20
	v_mfma_f32_32x32x16_bf16 v[16:31], v[210:213], v[218:221], v[16:31]
	v_mfma_f32_32x32x16_bf16 v[80:95], v[210:213], v[222:225], v[80:95]
	v_mfma_f32_32x32x16_bf16 v[0:15], v[214:217], v[218:221], v[0:15]
	v_mfma_f32_32x32x16_bf16 v[48:63], v[214:217], v[222:225], v[48:63]
	v_add_u32_e32 v228, v227, v174
	v_add_u32_e32 v230, v229, v174
	ds_read_b128 v[202:205], v228
	ds_read_b128 v[206:209], v228 offset:4096
	ds_read_b128 v[210:213], v228 offset:8192
	ds_read_b128 v[214:217], v228 offset:12288
	ds_read_b128 v[218:221], v230 offset:32768
	ds_read_b128 v[222:225], v230 offset:36864
	s_add_i32 s12, s12, 0x8000
	v_lshl_add_u64 v[158:159], v[158:159], 0, s[8:9]
	s_cmp_eq_u32 s12, 0xf8000
	s_cbranch_scc0 .Lrot129_loop
; template <int EPI, int PN>
; __device__ void gemm_phase(const Params& p, const u16* __restrict__ A, const u16* __restrict__ Bt, int nNt, char* smem) {
;     ...
;     for (int kt = 0; kt < 32; ++kt) {
;       asm volatile("s_waitcnt vmcnt(0)" ::: "memory");
;       __builtin_amdgcn_s_barrier();
;       const u16* Ab = ring + (kt & 1) * STG;
;       const u16* Bb = Ab + 16384;
;       u16* st = ring + ((kt + 1) & 1) * STG;
;       const bool pre = (kt + 1 < 32);
;       s16x8 af[2][4], bf[2][2];
;       auto ldfrag = [&](int ks, int slot) {
; #pragma unroll
;         for (int i = 0; i < 4; ++i) {
;           const int row = wr * 128 + i * 32 + lr;
;           af[slot][i] = *(const s16x8*)(Ab + row * 64 + (((ks * 2 + lh) ^ ((row >> 1) & 7)) * 8));
;         }
; #pragma unroll
;         for (int j = 0; j < 2; ++j) {
;           const int rowb = nh * 128 + wc * 64 + j * 32 + lr;
;           bf[slot][j] = *(const s16x8*)(Bb + rowb * 64 + (((ks * 2 + lh) ^ ((rowb >> 1) & 7)) * 8));
;         }
;       };
;       ldfrag(0, 0);
;       ldfrag(1, 1);
;       __builtin_amdgcn_sched_barrier(0);
; #pragma unroll
;       for (int ks = 0; ks < 4; ++ks) {
;         const int slot = ks & 1;
; #pragma unroll
;         for (int i = 0; i < 4; ++i) {
;           acc[i][0] = mfma32(af[slot][i], bf[slot][0], acc[i][0]);
;           acc[i][1] = mfma32(af[slot][i], bf[slot][1], acc[i][1]);
;           __builtin_amdgcn_sched_barrier(0);
;           if (pre && (i & 1) == 0) {
;             const int pi = ks * 2 + (i >> 1);
;             if (pi < 4) glds16(Ag0 + (size_t)pi * 64 * LDK + (kt + 1) * 64, st + (srow + 64 * pi) * 64 + sch * 8);
;             else glds16(Bg0 + (size_t)(pi - 4) * 64 * LDK + (kt + 1) * 64, st + 16384 + (srow + 64 * (pi - 4)) * 64 + sch * 8);
;             __builtin_amdgcn_sched_barrier(0);
;           }
;         }
;         if (ks + 2 < 4) { ldfrag(ks + 2, slot); __builtin_amdgcn_sched_barrier(0); }
;       }
	s_add_i32 s13, s12, 0xffff8000
	s_and_b32 s13, s13, 0x8000
	s_lshl_b32 s13, s13, 1
	v_lshl_or_b32 v128, v143, 1, s13
	v_lshl_add_u32 v149, v147, 1, s13
	s_and_b32 s98, s12, 0x8000
	s_lshl_b32 s98, s98, 1
	s_waitcnt lgkmcnt(7)
	v_mfma_f32_32x32x16_bf16 v[64:79], v[178:181], v[194:197], v[64:79]
	v_add3_u32 v226, s98, v162, v156
	s_waitcnt lgkmcnt(6)
	v_mfma_f32_32x32x16_bf16 v[112:127], v[178:181], v[198:201], v[112:127]
	v_readfirstlane_b32 s100, v226
	s_mov_b32 s20, m0
	s_add_i32 m0, s100, 0x8000
	s_nop 0
	global_load_lds_dwordx4 v[160:161], off
	v_mfma_f32_32x32x16_bf16 v[32:47], v[182:185], v[194:197], v[32:47]
	v_lshl_add_u64 v[178:179], v[160:161], 0, s[2:3]
	s_add_i32 m0, s100, 0xa000
	s_nop 0
	global_load_lds_dwordx4 v[178:179], off
	v_mfma_f32_32x32x16_bf16 v[96:111], v[182:185], v[198:201], v[96:111]
	v_lshl_add_u64 v[180:181], v[160:161], 0, s[4:5]
	s_add_i32 m0, s100, 0xc000
	s_nop 0
	global_load_lds_dwordx4 v[180:181], off
	v_mfma_f32_32x32x16_bf16 v[16:31], v[186:189], v[194:197], v[16:31]
	v_lshl_add_u64 v[178:179], v[160:161], 0, s[6:7]
	s_add_i32 m0, s100, 0xe000
	s_nop 0
	global_load_lds_dwordx4 v[178:179], off
	s_mov_b32 m0, s20
	v_mfma_f32_32x32x16_bf16 v[80:95], v[186:189], v[198:201], v[80:95]
	v_mfma_f32_32x32x16_bf16 v[0:15], v[190:193], v[194:197], v[0:15]
	v_mfma_f32_32x32x16_bf16 v[48:63], v[190:193], v[198:201], v[48:63]
	v_lshl_add_u64 v[160:161], v[160:161], 0, s[8:9]
	v_add_u32_e32 v177, v128, v175
	ds_read_b128 v[178:181], v177
	ds_read_b128 v[182:185], v177 offset:4096
	ds_read_b128 v[186:189], v177 offset:8192
	ds_read_b128 v[190:193], v177 offset:12288
	v_add_u32_e32 v177, v149, v175
	ds_read_b128 v[194:197], v177 offset:32768
	ds_read_b128 v[198:201], v177 offset:36864
	s_waitcnt lgkmcnt(7)
	v_mfma_f32_32x32x16_bf16 v[64:79], v[202:205], v[218:221], v[64:79]
	s_waitcnt lgkmcnt(6)
	v_mfma_f32_32x32x16_bf16 v[112:127], v[202:205], v[222:225], v[112:127]
	v_mfma_f32_32x32x16_bf16 v[32:47], v[206:209], v[218:221], v[32:47]
	v_mfma_f32_32x32x16_bf16 v[96:111], v[206:209], v[222:225], v[96:111]
	v_mfma_f32_32x32x16_bf16 v[16:31], v[210:213], v[218:221], v[16:31]
	v_mfma_f32_32x32x16_bf16 v[80:95], v[210:213], v[222:225], v[80:95]
	v_mfma_f32_32x32x16_bf16 v[0:15], v[214:217], v[218:221], v[0:15]
	v_mfma_f32_32x32x16_bf16 v[48:63], v[214:217], v[222:225], v[48:63]
	v_add_u32_e32 v128, v128, v176
	ds_read_b128 v[202:205], v128
	ds_read_b128 v[206:209], v128 offset:4096
	ds_read_b128 v[210:213], v128 offset:8192
	ds_read_b128 v[214:217], v128 offset:12288
	v_add_u32_e32 v128, v149, v176
	ds_read_b128 v[218:221], v128 offset:32768
	ds_read_b128 v[222:225], v128 offset:36864
	s_waitcnt lgkmcnt(7)
	v_mfma_f32_32x32x16_bf16 v[64:79], v[178:181], v[194:197], v[64:79]
	s_waitcnt lgkmcnt(6)
	v_mfma_f32_32x32x16_bf16 v[112:127], v[178:181], v[198:201], v[112:127]
	v_mfma_f32_32x32x16_bf16 v[32:47], v[182:185], v[194:197], v[32:47]
	v_mfma_f32_32x32x16_bf16 v[96:111], v[182:185], v[198:201], v[96:111]
	v_mfma_f32_32x32x16_bf16 v[16:31], v[186:189], v[194:197], v[16:31]
	v_mfma_f32_32x32x16_bf16 v[80:95], v[186:189], v[198:201], v[80:95]
	v_mfma_f32_32x32x16_bf16 v[0:15], v[190:193], v[194:197], v[0:15]
	v_mfma_f32_32x32x16_bf16 v[48:63], v[190:193], v[198:201], v[48:63]
	s_waitcnt lgkmcnt(1)
	v_mfma_f32_32x32x16_bf16 v[64:79], v[202:205], v[218:221], v[64:79]
	s_waitcnt lgkmcnt(0)
	v_mfma_f32_32x32x16_bf16 v[112:127], v[202:205], v[222:225], v[112:127]
	v_mfma_f32_32x32x16_bf16 v[32:47], v[206:209], v[218:221], v[32:47]
	v_mfma_f32_32x32x16_bf16 v[96:111], v[206:209], v[222:225], v[96:111]
	v_mfma_f32_32x32x16_bf16 v[16:31], v[210:213], v[218:221], v[16:31]
	v_mfma_f32_32x32x16_bf16 v[80:95], v[210:213], v[222:225], v[80:95]
	v_mfma_f32_32x32x16_bf16 v[0:15], v[214:217], v[218:221], v[0:15]
	v_mfma_f32_32x32x16_bf16 v[48:63], v[214:217], v[222:225], v[48:63]
	s_waitcnt vmcnt(0)
	s_barrier
	ds_read_b128 v[158:161], v164
	ds_read_b128 v[178:181], v164 offset:4096
	ds_read_b128 v[182:185], v164 offset:8192
	ds_read_b128 v[186:189], v164 offset:12288
	ds_read_b128 v[190:193], v165
	ds_read_b128 v[194:197], v165 offset:4096
	ds_read_b128 v[198:201], v166
	ds_read_b128 v[202:205], v166 offset:4096
	ds_read_b128 v[206:209], v166 offset:8192
	ds_read_b128 v[210:213], v166 offset:12288
	ds_read_b128 v[214:217], v168
	ds_read_b128 v[218:221], v168 offset:4096
	s_waitcnt lgkmcnt(7)
	v_mfma_f32_32x32x16_bf16 v[64:79], v[158:161], v[190:193], v[64:79]
	s_waitcnt lgkmcnt(6)
	v_mfma_f32_32x32x16_bf16 v[112:127], v[158:161], v[194:197], v[112:127]
	v_mfma_f32_32x32x16_bf16 v[32:47], v[178:181], v[190:193], v[32:47]
	v_mfma_f32_32x32x16_bf16 v[96:111], v[178:181], v[194:197], v[96:111]
	v_mfma_f32_32x32x16_bf16 v[16:31], v[182:185], v[190:193], v[16:31]
	v_mfma_f32_32x32x16_bf16 v[80:95], v[182:185], v[194:197], v[80:95]
	v_mfma_f32_32x32x16_bf16 v[0:15], v[186:189], v[190:193], v[0:15]
	v_mfma_f32_32x32x16_bf16 v[48:63], v[186:189], v[194:197], v[48:63]
	ds_read_b128 v[158:161], v169
	ds_read_b128 v[178:181], v169 offset:4096
	ds_read_b128 v[182:185], v169 offset:8192
	ds_read_b128 v[186:189], v169 offset:12288
	ds_read_b128 v[190:193], v170
	ds_read_b128 v[194:197], v170 offset:4096
	s_waitcnt lgkmcnt(7)
	v_mfma_f32_32x32x16_bf16 v[64:79], v[198:201], v[214:217], v[64:79]
	s_waitcnt lgkmcnt(6)
; template <int EPI, int PN>
; __device__ void gemm_phase(const Params& p, const u16* __restrict__ A, const u16* __restrict__ Bt, int nNt, char* smem) {
;     ...
;       for (int ks = 0; ks < 4; ++ks) {
;         const int slot = ks & 1;
; #pragma unroll
;         for (int i = 0; i < 4; ++i) {
;           acc[i][0] = mfma32(af[slot][i], bf[slot][0], acc[i][0]);
;           acc[i][1] = mfma32(af[slot][i], bf[slot][1], acc[i][1]);
;     ...
;     __syncthreads();
;     int mte = __builtin_amdgcn_readfirstlane(mt), nte = __builtin_amdgcn_readfirstlane(nt), lrE = lr, lhE = lh, laneE = lane;
;     asm volatile("" : "+s"(mte), "+s"(nte), "+v"(lrE), "+v"(lhE), "+v"(laneE));
;     unsigned char* et = (unsigned char*)smem + wv * 18432;
;     const int col0 = nte * 256 + nh * 128 + wc * 64;
;     const size_t row0 = (size_t)mte * 256 + wr * 128;
;     if (EPI == 1) {
; #pragma unroll
;       for (int j = 0; j < 2; ++j) {
; #pragma unroll
;         for (int i = 0; i < 4; ++i)
; #pragma unroll
;           for (int r = 0; r < 16; ++r) *(float*)(et + (i * 32 + accrow(r, lhE)) * 144 + lrE * 4) = acc[i][j][r];
; #pragma unroll
;         for (int it = 0; it < 16; ++it) {
;           const int c = it * 64 + laneE, row = c >> 3, seg = c & 7;
;           const float4 v = *(const float4*)(et + row * 144 + seg * 16);
;           const size_t g = (row0 + row) * DM + col0 + j * 32 + seg * 4;
;           const float4 xv = *(const float4*)(p.x + g);
;           const float4 hv = make_float4(xv.x + v.x, xv.y + v.y, xv.z + v.z, xv.w + v.w);
;           *(float4*)(p.out + g) = hv;
;           uint2 hb; hb.x = pack2(hv.x, hv.y); hb.y = pack2(hv.z, hv.w);
;           *(uint2*)(p.xn + (row0 + row) * LDK + col0 + j * 32 + seg * 4) = hb;
;         }
;       }
;     } else if (EPI == 0 && col0 >= NPROJ) {
; #pragma unroll
;       for (int i = 0; i < 4; ++i)
; #pragma unroll
;         for (int r = 0; r < 16; ++r) {
;           const size_t row = row0 + i * 32 + accrow(r, lhE);
;           const int col = col0 + lrE;
;           if (col < NIN) p.dtraw[row * 16 + (col - NPROJ)] = acc[i][0][r];
;         }
;     } else {
; #pragma unroll
;       for (int i = 0; i < 4; ++i)
; #pragma unroll
;         for (int j = 0; j < 2; ++j)
; #pragma unroll
;           for (int r = 0; r < 16; ++r) *(u16*)(et + (i * 32 + accrow(r, lhE)) * 144 + (j * 32 + lrE) * 2) = f2bf(acc[i][j][r]);
	v_mfma_f32_32x32x16_bf16 v[112:127], v[198:201], v[218:221], v[112:127]
	v_mfma_f32_32x32x16_bf16 v[32:47], v[202:205], v[214:217], v[32:47]
	v_mfma_f32_32x32x16_bf16 v[96:111], v[202:205], v[218:221], v[96:111]
	v_mfma_f32_32x32x16_bf16 v[16:31], v[206:209], v[214:217], v[16:31]
	v_mfma_f32_32x32x16_bf16 v[80:95], v[206:209], v[218:221], v[80:95]
	v_mfma_f32_32x32x16_bf16 v[0:15], v[210:213], v[214:217], v[0:15]
	v_mfma_f32_32x32x16_bf16 v[48:63], v[210:213], v[218:221], v[48:63]
	ds_read_b128 v[198:201], v171
	ds_read_b128 v[202:205], v171 offset:4096
	ds_read_b128 v[206:209], v171 offset:8192
	ds_read_b128 v[210:213], v171 offset:12288
	ds_read_b128 v[214:217], v172
	ds_read_b128 v[218:221], v172 offset:4096
	s_waitcnt lgkmcnt(7)
	v_mfma_f32_32x32x16_bf16 v[64:79], v[158:161], v[190:193], v[64:79]
	s_waitcnt lgkmcnt(6)
	v_mfma_f32_32x32x16_bf16 v[112:127], v[158:161], v[194:197], v[112:127]
	v_mfma_f32_32x32x16_bf16 v[32:47], v[178:181], v[190:193], v[32:47]
	v_mfma_f32_32x32x16_bf16 v[96:111], v[178:181], v[194:197], v[96:111]
	v_mfma_f32_32x32x16_bf16 v[16:31], v[182:185], v[190:193], v[16:31]
	v_mfma_f32_32x32x16_bf16 v[80:95], v[182:185], v[194:197], v[80:95]
	v_mfma_f32_32x32x16_bf16 v[0:15], v[186:189], v[190:193], v[0:15]
	v_mfma_f32_32x32x16_bf16 v[48:63], v[186:189], v[194:197], v[48:63]
	s_waitcnt lgkmcnt(1)
	v_mfma_f32_32x32x16_bf16 v[64:79], v[198:201], v[214:217], v[64:79]
	s_waitcnt lgkmcnt(0)
	v_mfma_f32_32x32x16_bf16 v[112:127], v[198:201], v[218:221], v[112:127]
	v_mfma_f32_32x32x16_bf16 v[32:47], v[202:205], v[214:217], v[32:47]
	v_mfma_f32_32x32x16_bf16 v[96:111], v[202:205], v[218:221], v[96:111]
	v_mfma_f32_32x32x16_bf16 v[16:31], v[206:209], v[214:217], v[16:31]
	v_mfma_f32_32x32x16_bf16 v[80:95], v[206:209], v[218:221], v[80:95]
	v_mfma_f32_32x32x16_bf16 v[0:15], v[210:213], v[214:217], v[0:15]
	v_mfma_f32_32x32x16_bf16 v[48:63], v[210:213], v[218:221], v[48:63]
	v_mov_b32_e32 v128, v139
	v_mov_b32_e32 v161, v137
	v_mov_b32_e32 v177, v135
	s_barrier
	s_nop 0
	v_lshl_add_u32 v160, s11, 8, v145
	s_ashr_i32 s11, s10, 31
	s_lshl_b64 s[10:11], s[10:11], 8
	v_mov_b32_e32 v159, s11
	v_or_b32_e32 v158, s10, v134
	v_cmp_gt_i32_e32 vcc, s14, v160
	s_and_saveexec_b64 s[10:11], vcc
	s_xor_b64 s[10:11], exec, s[10:11]
	s_cbranch_execz .LBB0_132
	v_lshlrev_b32_e32 v149, 1, v161
	v_mul_lo_u32 v128, v128, s15
	v_add3_u32 v128, v163, v149, v128
	v_cvt_pk_bf16_f32 v0, v0, s0
	v_cvt_pk_bf16_f32 v64, v64, s0
	v_cvt_pk_bf16_f32 v32, v32, s0
	v_cvt_pk_bf16_f32 v16, v16, s0
	ds_write_b16 v128, v0 offset:13824
	v_cvt_pk_bf16_f32 v0, v1, s0
	ds_write_b16 v128, v64
	v_cvt_pk_bf16_f32 v64, v65, s0
	ds_write_b16 v128, v32 offset:4608
	v_cvt_pk_bf16_f32 v32, v33, s0
	ds_write_b16 v128, v16 offset:9216
	v_cvt_pk_bf16_f32 v16, v17, s0
	ds_write_b16 v128, v0 offset:13968
	v_cvt_pk_bf16_f32 v0, v2, s0
	ds_write_b16 v128, v64 offset:144
	v_cvt_pk_bf16_f32 v64, v66, s0
	ds_write_b16 v128, v32 offset:4752
	v_cvt_pk_bf16_f32 v32, v34, s0
	ds_write_b16 v128, v16 offset:9360
	v_cvt_pk_bf16_f32 v16, v18, s0
	ds_write_b16 v128, v0 offset:14112
	v_cvt_pk_bf16_f32 v0, v3, s0
	ds_write_b16 v128, v64 offset:288
	v_cvt_pk_bf16_f32 v64, v67, s0
	ds_write_b16 v128, v32 offset:4896
	v_cvt_pk_bf16_f32 v32, v35, s0
	ds_write_b16 v128, v16 offset:9504
	v_cvt_pk_bf16_f32 v16, v19, s0
	ds_write_b16 v128, v0 offset:14256
	v_cvt_pk_bf16_f32 v0, v4, s0
	ds_write_b16 v128, v64 offset:432
	v_cvt_pk_bf16_f32 v64, v68, s0
	ds_write_b16 v128, v32 offset:5040
	v_cvt_pk_bf16_f32 v32, v36, s0
	ds_write_b16 v128, v16 offset:9648
	v_cvt_pk_bf16_f32 v16, v20, s0
	ds_write_b16 v128, v0 offset:14976
	v_cvt_pk_bf16_f32 v0, v5, s0
	ds_write_b16 v128, v64 offset:1152
	v_cvt_pk_bf16_f32 v64, v69, s0
	ds_write_b16 v128, v32 offset:5760
	v_cvt_pk_bf16_f32 v32, v37, s0
	ds_write_b16 v128, v16 offset:10368
	v_cvt_pk_bf16_f32 v16, v21, s0
	ds_write_b16 v128, v0 offset:15120
	v_cvt_pk_bf16_f32 v0, v6, s0
	ds_write_b16 v128, v64 offset:1296
	v_cvt_pk_bf16_f32 v64, v70, s0
	ds_write_b16 v128, v32 offset:5904
	v_cvt_pk_bf16_f32 v32, v38, s0
	ds_write_b16 v128, v16 offset:10512
	v_cvt_pk_bf16_f32 v16, v22, s0
	ds_write_b16 v128, v0 offset:15264
	v_cvt_pk_bf16_f32 v0, v7, s0
	ds_write_b16 v128, v64 offset:1440
	v_cvt_pk_bf16_f32 v64, v71, s0
	ds_write_b16 v128, v32 offset:6048
	v_cvt_pk_bf16_f32 v32, v39, s0
	ds_write_b16 v128, v16 offset:10656
	v_cvt_pk_bf16_f32 v16, v23, s0
	ds_write_b16 v128, v0 offset:15408
	v_cvt_pk_bf16_f32 v0, v8, s0
	ds_write_b16 v128, v64 offset:1584
	v_cvt_pk_bf16_f32 v64, v72, s0
	ds_write_b16 v128, v32 offset:6192
	v_cvt_pk_bf16_f32 v32, v40, s0
	ds_write_b16 v128, v16 offset:10800
	v_cvt_pk_bf16_f32 v16, v24, s0
	ds_write_b16 v128, v0 offset:16128
	v_cvt_pk_bf16_f32 v0, v9, s0
	ds_write_b16 v128, v64 offset:2304
	v_cvt_pk_bf16_f32 v64, v73, s0
	ds_write_b16 v128, v32 offset:6912
	v_cvt_pk_bf16_f32 v32, v41, s0
	ds_write_b16 v128, v16 offset:11520
	v_cvt_pk_bf16_f32 v16, v25, s0
	ds_write_b16 v128, v0 offset:16272
	v_cvt_pk_bf16_f32 v0, v10, s0
	ds_write_b16 v128, v64 offset:2448
	v_cvt_pk_bf16_f32 v64, v74, s0
	ds_write_b16 v128, v32 offset:7056
	v_cvt_pk_bf16_f32 v32, v42, s0
	ds_write_b16 v128, v16 offset:11664
	v_cvt_pk_bf16_f32 v16, v26, s0
	ds_write_b16 v128, v0 offset:16416
	v_cvt_pk_bf16_f32 v0, v11, s0
	ds_write_b16 v128, v64 offset:2592
	v_cvt_pk_bf16_f32 v64, v75, s0
	ds_write_b16 v128, v32 offset:7200
	v_cvt_pk_bf16_f32 v32, v43, s0
	ds_write_b16 v128, v16 offset:11808
	v_cvt_pk_bf16_f32 v16, v27, s0
	ds_write_b16 v128, v0 offset:16560
	v_cvt_pk_bf16_f32 v0, v12, s0
	ds_write_b16 v128, v64 offset:2736
	v_cvt_pk_bf16_f32 v64, v76, s0
; __device__ __forceinline__ int accrow(int reg, int lh) { return (reg & 3) + 8 * (reg >> 2) + 4 * lh; }
; template <int EPI, int PN>
; __device__ void gemm_phase(const Params& p, const u16* __restrict__ A, const u16* __restrict__ Bt, int nNt, char* smem) {
;     ...
; #pragma unroll
;       for (int i = 0; i < 4; ++i)
; #pragma unroll
;         for (int j = 0; j < 2; ++j)
; #pragma unroll
;           for (int r = 0; r < 16; ++r) *(u16*)(et + (i * 32 + accrow(r, lhE)) * 144 + (j * 32 + lrE) * 2) = f2bf(acc[i][j][r]);
; #pragma unroll
;       for (int it = 0; it < 16; ++it) {
;         const int c = it * 64 + laneE, row = c >> 3, seg = c & 7;
;         const uint4 v = *(const uint4*)(et + row * 144 + seg * 16);
;         if (EPI == 0) *(uint4*)(p.proj + (row0 + row) * NPROJ + col0 + seg * 8) = v;
;         else *(uint4*)(p.qp + (row0 + row) * DM + col0 + seg * 8) = v;
	ds_write_b16 v128, v32 offset:7344
	v_cvt_pk_bf16_f32 v32, v44, s0
	ds_write_b16 v128, v16 offset:11952
	v_cvt_pk_bf16_f32 v16, v28, s0
	ds_write_b16 v128, v0 offset:17280
	v_cvt_pk_bf16_f32 v0, v13, s0
	ds_write_b16 v128, v64 offset:3456
	v_cvt_pk_bf16_f32 v64, v77, s0
	ds_write_b16 v128, v32 offset:8064
	v_cvt_pk_bf16_f32 v32, v45, s0
	ds_write_b16 v128, v16 offset:12672
	v_cvt_pk_bf16_f32 v16, v29, s0
	ds_write_b16 v128, v0 offset:17424
	v_cvt_pk_bf16_f32 v0, v14, s0
	ds_write_b16 v128, v64 offset:3600
	v_cvt_pk_bf16_f32 v64, v78, s0
	ds_write_b16 v128, v32 offset:8208
	v_cvt_pk_bf16_f32 v32, v46, s0
	ds_write_b16 v128, v16 offset:12816
	v_cvt_pk_bf16_f32 v16, v30, s0
	ds_write_b16 v128, v0 offset:17568
	v_cvt_pk_bf16_f32 v0, v15, s0
	ds_write_b16 v128, v64 offset:3744
	v_cvt_pk_bf16_f32 v64, v79, s0
	ds_write_b16 v128, v32 offset:8352
	v_cvt_pk_bf16_f32 v32, v47, s0
	ds_write_b16 v128, v16 offset:12960
	v_cvt_pk_bf16_f32 v16, v31, s0
	ds_write_b16 v128, v0 offset:17712
	v_cvt_pk_bf16_f32 v0, v48, s0
	ds_write_b16 v128, v64 offset:3888
	v_cvt_pk_bf16_f32 v64, v112, s0
	ds_write_b16 v128, v32 offset:8496
	v_cvt_pk_bf16_f32 v32, v96, s0
	ds_write_b16 v128, v16 offset:13104
	v_cvt_pk_bf16_f32 v16, v80, s0
	ds_write_b16 v128, v0 offset:13888
	v_cvt_pk_bf16_f32 v0, v49, s0
	ds_write_b16 v128, v64 offset:64
	v_cvt_pk_bf16_f32 v64, v113, s0
	ds_write_b16 v128, v32 offset:4672
	v_cvt_pk_bf16_f32 v32, v97, s0
	ds_write_b16 v128, v16 offset:9280
	v_cvt_pk_bf16_f32 v16, v81, s0
	ds_write_b16 v128, v0 offset:14032
	v_cvt_pk_bf16_f32 v0, v50, s0
	ds_write_b16 v128, v64 offset:208
	v_cvt_pk_bf16_f32 v64, v114, s0
	ds_write_b16 v128, v32 offset:4816
	v_cvt_pk_bf16_f32 v32, v98, s0
	ds_write_b16 v128, v16 offset:9424
	v_cvt_pk_bf16_f32 v16, v82, s0
	ds_write_b16 v128, v0 offset:14176
	v_cvt_pk_bf16_f32 v0, v51, s0
	ds_write_b16 v128, v64 offset:352
	v_cvt_pk_bf16_f32 v64, v115, s0
	ds_write_b16 v128, v32 offset:4960
	v_cvt_pk_bf16_f32 v32, v99, s0
	ds_write_b16 v128, v16 offset:9568
	v_cvt_pk_bf16_f32 v16, v83, s0
	ds_write_b16 v128, v0 offset:14320
	v_cvt_pk_bf16_f32 v0, v52, s0
	ds_write_b16 v128, v64 offset:496
	v_cvt_pk_bf16_f32 v64, v116, s0
	ds_write_b16 v128, v32 offset:5104
	v_cvt_pk_bf16_f32 v32, v100, s0
	ds_write_b16 v128, v16 offset:9712
	v_cvt_pk_bf16_f32 v16, v84, s0
	ds_write_b16 v128, v0 offset:15040
	v_cvt_pk_bf16_f32 v0, v53, s0
	ds_write_b16 v128, v64 offset:1216
	v_cvt_pk_bf16_f32 v64, v117, s0
	ds_write_b16 v128, v32 offset:5824
	v_cvt_pk_bf16_f32 v32, v101, s0
	ds_write_b16 v128, v16 offset:10432
	v_cvt_pk_bf16_f32 v16, v85, s0
	ds_write_b16 v128, v0 offset:15184
	v_cvt_pk_bf16_f32 v0, v54, s0
	ds_write_b16 v128, v64 offset:1360
	v_cvt_pk_bf16_f32 v64, v118, s0
	ds_write_b16 v128, v32 offset:5968
	v_cvt_pk_bf16_f32 v32, v102, s0
	ds_write_b16 v128, v16 offset:10576
	v_cvt_pk_bf16_f32 v16, v86, s0
	ds_write_b16 v128, v0 offset:15328
	v_cvt_pk_bf16_f32 v0, v55, s0
	ds_write_b16 v128, v64 offset:1504
	v_cvt_pk_bf16_f32 v64, v119, s0
	ds_write_b16 v128, v32 offset:6112
	v_cvt_pk_bf16_f32 v32, v103, s0
	ds_write_b16 v128, v16 offset:10720
	v_cvt_pk_bf16_f32 v16, v87, s0
	ds_write_b16 v128, v0 offset:15472
	v_cvt_pk_bf16_f32 v0, v56, s0
	ds_write_b16 v128, v64 offset:1648
	v_cvt_pk_bf16_f32 v64, v120, s0
	ds_write_b16 v128, v32 offset:6256
	v_cvt_pk_bf16_f32 v32, v104, s0
	ds_write_b16 v128, v16 offset:10864
	v_cvt_pk_bf16_f32 v16, v88, s0
	ds_write_b16 v128, v0 offset:16192
	v_cvt_pk_bf16_f32 v0, v57, s0
	ds_write_b16 v128, v64 offset:2368
	v_cvt_pk_bf16_f32 v64, v121, s0
	ds_write_b16 v128, v32 offset:6976
	v_cvt_pk_bf16_f32 v32, v105, s0
	ds_write_b16 v128, v16 offset:11584
	v_cvt_pk_bf16_f32 v16, v89, s0
	ds_write_b16 v128, v0 offset:16336
	v_cvt_pk_bf16_f32 v0, v58, s0
	ds_write_b16 v128, v64 offset:2512
	v_cvt_pk_bf16_f32 v64, v122, s0
	ds_write_b16 v128, v32 offset:7120
	v_cvt_pk_bf16_f32 v32, v106, s0
	ds_write_b16 v128, v16 offset:11728
	v_cvt_pk_bf16_f32 v16, v90, s0
	ds_write_b16 v128, v0 offset:16480
	v_cvt_pk_bf16_f32 v0, v59, s0
	ds_write_b16 v128, v64 offset:2656
	v_cvt_pk_bf16_f32 v64, v123, s0
	ds_write_b16 v128, v32 offset:7264
	v_cvt_pk_bf16_f32 v32, v107, s0
	ds_write_b16 v128, v16 offset:11872
	v_cvt_pk_bf16_f32 v16, v91, s0
	ds_write_b16 v128, v0 offset:16624
	v_cvt_pk_bf16_f32 v0, v60, s0
	ds_write_b16 v128, v64 offset:2800
	v_cvt_pk_bf16_f32 v64, v124, s0
	ds_write_b16 v128, v32 offset:7408
	v_cvt_pk_bf16_f32 v32, v108, s0
	ds_write_b16 v128, v16 offset:12016
	v_cvt_pk_bf16_f32 v16, v92, s0
	ds_write_b16 v128, v0 offset:17344
	v_cvt_pk_bf16_f32 v0, v61, s0
	ds_write_b16 v128, v64 offset:3520
	v_cvt_pk_bf16_f32 v64, v125, s0
	ds_write_b16 v128, v32 offset:8128
	v_cvt_pk_bf16_f32 v32, v109, s0
	ds_write_b16 v128, v16 offset:12736
	v_cvt_pk_bf16_f32 v16, v93, s0
	ds_write_b16 v128, v0 offset:17488
	v_cvt_pk_bf16_f32 v0, v62, s0
	ds_write_b16 v128, v64 offset:3664
	v_cvt_pk_bf16_f32 v64, v126, s0
	ds_write_b16 v128, v32 offset:8272
	v_cvt_pk_bf16_f32 v32, v110, s0
	ds_write_b16 v128, v16 offset:12880
	v_cvt_pk_bf16_f32 v16, v94, s0
	ds_write_b16 v128, v0 offset:17632
	v_cvt_pk_bf16_f32 v0, v63, s0
	ds_write_b16 v128, v64 offset:3808
	v_cvt_pk_bf16_f32 v64, v127, s0
	ds_write_b16 v128, v32 offset:8416
	v_cvt_pk_bf16_f32 v32, v111, s0
	ds_write_b16 v128, v16 offset:13024
	v_cvt_pk_bf16_f32 v16, v95, s0
	ds_write_b16 v128, v0 offset:17776
	v_lshlrev_b32_e32 v0, 4, v177
	ds_write_b16 v128, v64 offset:3952
	ds_write_b16 v128, v32 offset:8560
	ds_write_b16 v128, v16 offset:13168
	v_and_b32_e32 v128, 0x70, v0
	v_add_u32_e32 v0, v163, v128
	v_ashrrev_i32_e32 v6, 3, v177
	v_readlane_b32 s36, v253, 39
	v_mad_u64_u32 v[2:3], s[12:13], v6, s16, v[0:1]
	v_ashrrev_i32_e32 v7, 31, v6
	v_readlane_b32 s40, v253, 43
	v_readlane_b32 s41, v253, 44
	ds_read_b128 v[2:5], v2
	v_lshl_add_u64 v[6:7], v[158:159], 0, v[6:7]
	v_mov_b64_e32 v[10:11], s[40:41]
	v_ashrrev_i32_e32 v161, 31, v160
	v_mad_u64_u32 v[8:9], s[12:13], v6, s17, v[10:11]
	v_mad_i32_i24 v9, v7, s17, v9
	v_lshlrev_b64 v[12:13], 1, v[160:161]
	v_add_u32_e32 v1, 64, v177
	v_lshl_add_u64 v[6:7], v[8:9], 0, v[12:13]
	v_ashrrev_i32_e32 v16, 3, v1
	v_lshl_add_u64 v[14:15], v[6:7], 0, v[128:129]
	v_mad_u64_u32 v[6:7], s[12:13], v16, s16, v[0:1]
	v_ashrrev_i32_e32 v17, 31, v16
	ds_read_b128 v[6:9], v6
	s_waitcnt lgkmcnt(1)
; template <int EPI, int PN>
; __device__ void gemm_phase(const Params& p, const u16* __restrict__ A, const u16* __restrict__ Bt, int nNt, char* smem) {
;     ...
;       for (int it = 0; it < 16; ++it) {
;         const int c = it * 64 + laneE, row = c >> 3, seg = c & 7;
;         const uint4 v = *(const uint4*)(et + row * 144 + seg * 16);
;         if (EPI == 0) *(uint4*)(p.proj + (row0 + row) * NPROJ + col0 + seg * 8) = v;
;         else *(uint4*)(p.qp + (row0 + row) * DM + col0 + seg * 8) = v;
;       }
	global_store_dwordx4 v[14:15], v[2:5], off
	v_add_u32_e32 v1, 0x80, v177
	v_readlane_b32 s37, v253, 40
	v_lshl_add_u64 v[2:3], v[158:159], 0, v[16:17]
	v_mad_u64_u32 v[4:5], s[12:13], v2, s17, v[10:11]
	v_mad_i32_i24 v5, v3, s17, v5
	v_lshl_add_u64 v[2:3], v[4:5], 0, v[12:13]
	v_lshl_add_u64 v[2:3], v[2:3], 0, v[128:129]
	s_waitcnt lgkmcnt(0)
	global_store_dwordx4 v[2:3], v[6:9], off
	v_readlane_b32 s38, v253, 41
	v_readlane_b32 s39, v253, 42
	v_ashrrev_i32_e32 v6, 3, v1
	v_mad_u64_u32 v[2:3], s[12:13], v6, s16, v[0:1]
	v_ashrrev_i32_e32 v7, 31, v6
	ds_read_b128 v[2:5], v2
	v_lshl_add_u64 v[6:7], v[158:159], 0, v[6:7]
	v_mad_u64_u32 v[8:9], s[12:13], v6, s17, v[10:11]
	v_mad_i32_i24 v9, v7, s17, v9
	v_add_u32_e32 v1, 0xc0, v177
	v_lshl_add_u64 v[6:7], v[8:9], 0, v[12:13]
	v_ashrrev_i32_e32 v16, 3, v1
	v_lshl_add_u64 v[14:15], v[6:7], 0, v[128:129]
	v_mad_u64_u32 v[6:7], s[12:13], v16, s16, v[0:1]
	v_ashrrev_i32_e32 v17, 31, v16
	ds_read_b128 v[6:9], v6
	s_waitcnt lgkmcnt(1)
	global_store_dwordx4 v[14:15], v[2:5], off
	v_add_u32_e32 v1, 0x100, v177
	v_readlane_b32 s42, v253, 45
	v_lshl_add_u64 v[2:3], v[158:159], 0, v[16:17]
	v_mad_u64_u32 v[4:5], s[12:13], v2, s17, v[10:11]
	v_mad_i32_i24 v5, v3, s17, v5
	v_lshl_add_u64 v[2:3], v[4:5], 0, v[12:13]
	v_lshl_add_u64 v[2:3], v[2:3], 0, v[128:129]
	s_waitcnt lgkmcnt(0)
	global_store_dwordx4 v[2:3], v[6:9], off
	v_readlane_b32 s43, v253, 46
	v_readlane_b32 s44, v253, 47
	v_ashrrev_i32_e32 v6, 3, v1
	v_mad_u64_u32 v[2:3], s[12:13], v6, s16, v[0:1]
	v_ashrrev_i32_e32 v7, 31, v6
	ds_read_b128 v[2:5], v2
	v_lshl_add_u64 v[6:7], v[158:159], 0, v[6:7]
	v_mad_u64_u32 v[8:9], s[12:13], v6, s17, v[10:11]
	v_mad_i32_i24 v9, v7, s17, v9
	v_add_u32_e32 v1, 0x140, v177
	v_lshl_add_u64 v[6:7], v[8:9], 0, v[12:13]
	v_ashrrev_i32_e32 v16, 3, v1
	v_lshl_add_u64 v[14:15], v[6:7], 0, v[128:129]
	v_mad_u64_u32 v[6:7], s[12:13], v16, s16, v[0:1]
	v_ashrrev_i32_e32 v17, 31, v16
	ds_read_b128 v[6:9], v6
	s_waitcnt lgkmcnt(1)
	global_store_dwordx4 v[14:15], v[2:5], off
	v_add_u32_e32 v1, 0x180, v177
	v_readlane_b32 s45, v253, 48
	v_lshl_add_u64 v[2:3], v[158:159], 0, v[16:17]
	v_mad_u64_u32 v[4:5], s[12:13], v2, s17, v[10:11]
	v_mad_i32_i24 v5, v3, s17, v5
	v_lshl_add_u64 v[2:3], v[4:5], 0, v[12:13]
	v_lshl_add_u64 v[2:3], v[2:3], 0, v[128:129]
	s_waitcnt lgkmcnt(0)
	global_store_dwordx4 v[2:3], v[6:9], off
	v_readlane_b32 s46, v253, 49
	v_readlane_b32 s47, v253, 50
	v_ashrrev_i32_e32 v6, 3, v1
	v_mad_u64_u32 v[2:3], s[12:13], v6, s16, v[0:1]
	v_ashrrev_i32_e32 v7, 31, v6
	ds_read_b128 v[2:5], v2
	v_lshl_add_u64 v[6:7], v[158:159], 0, v[6:7]
	v_mad_u64_u32 v[8:9], s[12:13], v6, s17, v[10:11]
	v_mad_i32_i24 v9, v7, s17, v9
	v_add_u32_e32 v1, 0x1c0, v177
	v_lshl_add_u64 v[6:7], v[8:9], 0, v[12:13]
	v_ashrrev_i32_e32 v16, 3, v1
	v_lshl_add_u64 v[14:15], v[6:7], 0, v[128:129]
	v_mad_u64_u32 v[6:7], s[12:13], v16, s16, v[0:1]
	v_ashrrev_i32_e32 v17, 31, v16
	ds_read_b128 v[6:9], v6
	s_waitcnt lgkmcnt(1)
	global_store_dwordx4 v[14:15], v[2:5], off
	v_add_u32_e32 v1, 0x200, v177
	v_readlane_b32 s48, v253, 51
	v_lshl_add_u64 v[2:3], v[158:159], 0, v[16:17]
	v_mad_u64_u32 v[4:5], s[12:13], v2, s17, v[10:11]
	v_mad_i32_i24 v5, v3, s17, v5
	v_lshl_add_u64 v[2:3], v[4:5], 0, v[12:13]
	v_lshl_add_u64 v[2:3], v[2:3], 0, v[128:129]
	s_waitcnt lgkmcnt(0)
; template <int EPI, int PN>
; __device__ void gemm_phase(const Params& p, const u16* __restrict__ A, const u16* __restrict__ Bt, int nNt, char* smem) {
;     ...
;       for (int it = 0; it < 16; ++it) {
;         const int c = it * 64 + laneE, row = c >> 3, seg = c & 7;
;         const uint4 v = *(const uint4*)(et + row * 144 + seg * 16);
;         if (EPI == 0) *(uint4*)(p.proj + (row0 + row) * NPROJ + col0 + seg * 8) = v;
;         else *(uint4*)(p.qp + (row0 + row) * DM + col0 + seg * 8) = v;
;       }
	global_store_dwordx4 v[2:3], v[6:9], off
	v_readlane_b32 s49, v253, 52
	v_readlane_b32 s50, v253, 53
	v_ashrrev_i32_e32 v6, 3, v1
	v_mad_u64_u32 v[2:3], s[12:13], v6, s16, v[0:1]
	v_ashrrev_i32_e32 v7, 31, v6
	ds_read_b128 v[2:5], v2
	v_lshl_add_u64 v[6:7], v[158:159], 0, v[6:7]
	v_mad_u64_u32 v[8:9], s[12:13], v6, s17, v[10:11]
	v_mad_i32_i24 v9, v7, s17, v9
	v_add_u32_e32 v1, 0x240, v177
	v_lshl_add_u64 v[6:7], v[8:9], 0, v[12:13]
	v_ashrrev_i32_e32 v16, 3, v1
	v_lshl_add_u64 v[14:15], v[6:7], 0, v[128:129]
	v_mad_u64_u32 v[6:7], s[12:13], v16, s16, v[0:1]
	v_ashrrev_i32_e32 v17, 31, v16
	ds_read_b128 v[6:9], v6
	s_waitcnt lgkmcnt(1)
	global_store_dwordx4 v[14:15], v[2:5], off
	v_add_u32_e32 v1, 0x280, v177
	v_readlane_b32 s51, v253, 54
	v_lshl_add_u64 v[2:3], v[158:159], 0, v[16:17]
	v_mad_u64_u32 v[4:5], s[12:13], v2, s17, v[10:11]
	v_mad_i32_i24 v5, v3, s17, v5
	v_lshl_add_u64 v[2:3], v[4:5], 0, v[12:13]
	v_lshl_add_u64 v[2:3], v[2:3], 0, v[128:129]
	s_waitcnt lgkmcnt(0)
	global_store_dwordx4 v[2:3], v[6:9], off
	s_nop 1
	v_ashrrev_i32_e32 v6, 3, v1
	v_mad_u64_u32 v[2:3], s[12:13], v6, s16, v[0:1]
	v_ashrrev_i32_e32 v7, 31, v6
	ds_read_b128 v[2:5], v2
	v_lshl_add_u64 v[6:7], v[158:159], 0, v[6:7]
	v_mad_u64_u32 v[8:9], s[12:13], v6, s17, v[10:11]
	v_mad_i32_i24 v9, v7, s17, v9
	v_add_u32_e32 v1, 0x2c0, v177
	v_lshl_add_u64 v[6:7], v[8:9], 0, v[12:13]
	v_ashrrev_i32_e32 v16, 3, v1
	v_lshl_add_u64 v[14:15], v[6:7], 0, v[128:129]
	v_mad_u64_u32 v[6:7], s[12:13], v16, s16, v[0:1]
	v_ashrrev_i32_e32 v17, 31, v16
	ds_read_b128 v[6:9], v6
	s_waitcnt lgkmcnt(1)
	global_store_dwordx4 v[14:15], v[2:5], off
	v_add_u32_e32 v1, 0x300, v177
	s_nop 0
	v_lshl_add_u64 v[2:3], v[158:159], 0, v[16:17]
	v_mad_u64_u32 v[4:5], s[12:13], v2, s17, v[10:11]
	v_mad_i32_i24 v5, v3, s17, v5
	v_lshl_add_u64 v[2:3], v[4:5], 0, v[12:13]
	v_lshl_add_u64 v[2:3], v[2:3], 0, v[128:129]
	s_waitcnt lgkmcnt(0)
	global_store_dwordx4 v[2:3], v[6:9], off
	s_nop 1
	v_ashrrev_i32_e32 v6, 3, v1
	v_mad_u64_u32 v[2:3], s[12:13], v6, s16, v[0:1]
	v_ashrrev_i32_e32 v7, 31, v6
	ds_read_b128 v[2:5], v2
	v_lshl_add_u64 v[6:7], v[158:159], 0, v[6:7]
	v_mad_u64_u32 v[8:9], s[12:13], v6, s17, v[10:11]
	v_mad_i32_i24 v9, v7, s17, v9
	v_add_u32_e32 v1, 0x340, v177
	v_lshl_add_u64 v[6:7], v[8:9], 0, v[12:13]
	v_ashrrev_i32_e32 v16, 3, v1
	v_lshl_add_u64 v[14:15], v[6:7], 0, v[128:129]
	v_mad_u64_u32 v[6:7], s[12:13], v16, s16, v[0:1]
	v_ashrrev_i32_e32 v17, 31, v16
	ds_read_b128 v[6:9], v6
	s_waitcnt lgkmcnt(1)
	global_store_dwordx4 v[14:15], v[2:5], off
	v_add_u32_e32 v1, 0x380, v177
	s_nop 0
	v_lshl_add_u64 v[2:3], v[158:159], 0, v[16:17]
	v_mad_u64_u32 v[4:5], s[12:13], v2, s17, v[10:11]
	v_mad_i32_i24 v5, v3, s17, v5
	v_lshl_add_u64 v[2:3], v[4:5], 0, v[12:13]
	v_lshl_add_u64 v[2:3], v[2:3], 0, v[128:129]
	s_waitcnt lgkmcnt(0)
	global_store_dwordx4 v[2:3], v[6:9], off
	s_nop 1
	v_ashrrev_i32_e32 v6, 3, v1
	v_mad_u64_u32 v[2:3], s[12:13], v6, s16, v[0:1]
	v_ashrrev_i32_e32 v7, 31, v6
	ds_read_b128 v[2:5], v2
	v_lshl_add_u64 v[6:7], v[158:159], 0, v[6:7]
	v_mad_u64_u32 v[8:9], s[12:13], v6, s17, v[10:11]
	v_add_u32_e32 v1, 0x3c0, v177
	v_mad_i32_i24 v9, v7, s17, v9
	v_ashrrev_i32_e32 v16, 3, v1
	v_lshl_add_u64 v[6:7], v[8:9], 0, v[12:13]
	v_mad_u64_u32 v[0:1], s[12:13], v16, s16, v[0:1]
	v_ashrrev_i32_e32 v17, 31, v16
	v_lshl_add_u64 v[14:15], v[6:7], 0, v[128:129]
	ds_read_b128 v[6:9], v0
	v_lshl_add_u64 v[0:1], v[158:159], 0, v[16:17]
	s_waitcnt lgkmcnt(1)
	global_store_dwordx4 v[14:15], v[2:5], off
	s_nop 1
	v_mad_u64_u32 v[2:3], s[12:13], v0, s17, v[10:11]
	v_mad_i32_i24 v3, v1, s17, v3
	v_lshl_add_u64 v[0:1], v[2:3], 0, v[12:13]
	v_lshl_add_u64 v[0:1], v[0:1], 0, v[128:129]
	s_waitcnt lgkmcnt(0)
	global_store_dwordx4 v[0:1], v[6:9], off

; template <int EPI, int PN>
; __device__ void gemm_phase(const Params& p, const u16* __restrict__ A, const u16* __restrict__ Bt, int nNt, char* smem) {
;     ...
;     for (int kt = 0; kt < 32; ++kt) {
;       asm volatile("s_waitcnt vmcnt(0)" ::: "memory");
;       __builtin_amdgcn_s_barrier();
;       const u16* Ab = ring + (kt & 1) * STG;
;       const u16* Bb = Ab + 16384;
;       u16* st = ring + ((kt + 1) & 1) * STG;
;       const bool pre = (kt + 1 < 32);
;       s16x8 af[2][4], bf[2][2];
;       auto ldfrag = [&](int ks, int slot) {
; #pragma unroll
;         for (int i = 0; i < 4; ++i) {
;           const int row = wr * 128 + i * 32 + lr;
;           af[slot][i] = *(const s16x8*)(Ab + row * 64 + (((ks * 2 + lh) ^ ((row >> 1) & 7)) * 8));
;         }
; #pragma unroll
;         for (int j = 0; j < 2; ++j) {
;           const int rowb = nh * 128 + wc * 64 + j * 32 + lr;
;           bf[slot][j] = *(const s16x8*)(Bb + rowb * 64 + (((ks * 2 + lh) ^ ((rowb >> 1) & 7)) * 8));
;         }
;       };
;       ldfrag(0, 0);
;       ldfrag(1, 1);
;       __builtin_amdgcn_sched_barrier(0);
; #pragma unroll
;       for (int ks = 0; ks < 4; ++ks) {
;         const int slot = ks & 1;
; #pragma unroll
;         for (int i = 0; i < 4; ++i) {
;           acc[i][0] = mfma32(af[slot][i], bf[slot][0], acc[i][0]);
;           acc[i][1] = mfma32(af[slot][i], bf[slot][1], acc[i][1]);
;           __builtin_amdgcn_sched_barrier(0);
;           if (pre && (i & 1) == 0) {
;             const int pi = ks * 2 + (i >> 1);
;             if (pi < 4) glds16(Ag0 + (size_t)pi * 64 * LDK + (kt + 1) * 64, st + (srow + 64 * pi) * 64 + sch * 8);
;             else glds16(Bg0 + (size_t)(pi - 4) * 64 * LDK + (kt + 1) * 64, st + 16384 + (srow + 64 * (pi - 4)) * 64 + sch * 8);
;             __builtin_amdgcn_sched_barrier(0);
;           }
;         }
;         if (ks + 2 < 4) { ldfrag(ks + 2, slot); __builtin_amdgcn_sched_barrier(0); }
;       }
.Lrot666_loop:
	s_add_i32 s18, s17, 0xffff8000
	s_and_b32 s18, s18, 0x8000
	s_lshl_b32 s18, s18, 1
	v_lshl_or_b32 v128, v143, 1, s18
	v_lshl_add_u32 v166, v147, 1, s18
	s_and_b32 s98, s17, 0x8000
	s_lshl_b32 s98, s98, 1
	s_waitcnt lgkmcnt(7)
	v_mfma_f32_32x32x16_bf16 v[112:127], v[162:165], v[180:183], v[112:127]
	v_add3_u32 v148, s98, v224, v156
	s_waitcnt lgkmcnt(6)
	v_mfma_f32_32x32x16_bf16 v[48:63], v[162:165], v[184:187], v[48:63]
	v_readfirstlane_b32 s100, v148
	s_mov_b32 s19, m0
	s_add_i32 m0, s100, 0x8000
	s_nop 0
	global_load_lds_dwordx4 v[160:161], off
	v_mfma_f32_32x32x16_bf16 v[96:111], v[168:171], v[180:183], v[96:111]
	v_lshl_add_u64 v[162:163], v[160:161], 0, s[4:5]
	s_add_i32 m0, s100, 0xa000
	s_nop 0
	global_load_lds_dwordx4 v[162:163], off
	v_mfma_f32_32x32x16_bf16 v[32:47], v[168:171], v[184:187], v[32:47]
	v_lshl_add_u64 v[164:165], v[160:161], 0, s[6:7]
	s_add_i32 m0, s100, 0xc000
	s_nop 0
	global_load_lds_dwordx4 v[164:165], off
	v_mfma_f32_32x32x16_bf16 v[80:95], v[172:175], v[180:183], v[80:95]
	v_lshl_add_u64 v[162:163], v[160:161], 0, s[8:9]
	s_add_i32 m0, s100, 0xe000
	s_nop 0
	global_load_lds_dwordx4 v[162:163], off
	s_mov_b32 m0, s19
	v_mfma_f32_32x32x16_bf16 v[16:31], v[172:175], v[184:187], v[16:31]
	v_mfma_f32_32x32x16_bf16 v[64:79], v[176:179], v[180:183], v[64:79]
	v_mfma_f32_32x32x16_bf16 v[0:15], v[176:179], v[184:187], v[0:15]
	v_lshl_add_u64 v[160:161], v[160:161], 0, s[10:11]
	v_add_u32_e32 v176, v128, v236
	ds_read_b128 v[162:165], v176
	ds_read_b128 v[168:171], v176 offset:4096
	ds_read_b128 v[172:175], v176 offset:8192
	ds_read_b128 v[176:179], v176 offset:12288
	v_add_u32_e32 v184, v166, v236
	ds_read_b128 v[180:183], v184 offset:32768
	ds_read_b128 v[184:187], v184 offset:36864
	s_waitcnt lgkmcnt(7)
	v_mfma_f32_32x32x16_bf16 v[112:127], v[188:191], v[204:207], v[112:127]
	s_waitcnt lgkmcnt(6)
	v_mfma_f32_32x32x16_bf16 v[48:63], v[188:191], v[208:211], v[48:63]
	v_mfma_f32_32x32x16_bf16 v[96:111], v[192:195], v[204:207], v[96:111]
	v_mfma_f32_32x32x16_bf16 v[32:47], v[192:195], v[208:211], v[32:47]
	v_mfma_f32_32x32x16_bf16 v[80:95], v[196:199], v[204:207], v[80:95]
	v_mfma_f32_32x32x16_bf16 v[16:31], v[196:199], v[208:211], v[16:31]
	v_mfma_f32_32x32x16_bf16 v[64:79], v[200:203], v[204:207], v[64:79]
	v_mfma_f32_32x32x16_bf16 v[0:15], v[200:203], v[208:211], v[0:15]
	v_add_u32_e32 v128, v128, v237
	ds_read_b128 v[188:191], v128
	ds_read_b128 v[192:195], v128 offset:4096
	ds_read_b128 v[196:199], v128 offset:8192
	ds_read_b128 v[200:203], v128 offset:12288
	v_add_u32_e32 v128, v166, v237
	ds_read_b128 v[204:207], v128 offset:32768
	ds_read_b128 v[208:211], v128 offset:36864
	s_waitcnt lgkmcnt(7)
	v_mfma_f32_32x32x16_bf16 v[112:127], v[162:165], v[180:183], v[112:127]
	s_waitcnt lgkmcnt(6)
	v_mfma_f32_32x32x16_bf16 v[48:63], v[162:165], v[184:187], v[48:63]
	v_mfma_f32_32x32x16_bf16 v[96:111], v[168:171], v[180:183], v[96:111]
	v_mfma_f32_32x32x16_bf16 v[32:47], v[168:171], v[184:187], v[32:47]
	v_mfma_f32_32x32x16_bf16 v[80:95], v[172:175], v[180:183], v[80:95]
	v_mfma_f32_32x32x16_bf16 v[16:31], v[172:175], v[184:187], v[16:31]
	v_mfma_f32_32x32x16_bf16 v[64:79], v[176:179], v[180:183], v[64:79]
	v_mfma_f32_32x32x16_bf16 v[0:15], v[176:179], v[184:187], v[0:15]
	s_waitcnt vmcnt(0) lgkmcnt(0)
	s_barrier
	v_lshl_or_b32 v212, v143, 1, s98
	v_lshl_add_u32 v213, v147, 1, s98
	v_add_u32_e32 v149, v212, v234
	v_add_u32_e32 v148, v213, v234
	ds_read_b128 v[162:165], v149
	ds_read_b128 v[168:171], v149 offset:4096
	ds_read_b128 v[172:175], v149 offset:8192
	ds_read_b128 v[176:179], v149 offset:12288
	ds_read_b128 v[180:183], v148 offset:32768
	ds_read_b128 v[184:187], v148 offset:36864
	v_add3_u32 v148, s18, v224, v156
	v_mfma_f32_32x32x16_bf16 v[112:127], v[188:191], v[204:207], v[112:127]
	v_readfirstlane_b32 s99, v148
	s_mov_b32 s19, m0
	s_mov_b32 m0, s99
	s_nop 0
	global_load_lds_dwordx4 v[158:159], off
	v_mfma_f32_32x32x16_bf16 v[48:63], v[188:191], v[208:211], v[48:63]
	v_lshl_add_u64 v[188:189], v[158:159], 0, s[4:5]
	s_add_i32 m0, s99, 0x2000
	s_nop 0
	global_load_lds_dwordx4 v[188:189], off
	v_mfma_f32_32x32x16_bf16 v[96:111], v[192:195], v[204:207], v[96:111]
	v_lshl_add_u64 v[190:191], v[158:159], 0, s[6:7]
	s_add_i32 m0, s99, 0x4000
	s_nop 0
	global_load_lds_dwordx4 v[190:191], off
	v_mfma_f32_32x32x16_bf16 v[32:47], v[192:195], v[208:211], v[32:47]
	v_lshl_add_u64 v[188:189], v[158:159], 0, s[8:9]
	s_add_i32 m0, s99, 0x6000
	s_nop 0
	global_load_lds_dwordx4 v[188:189], off
	s_mov_b32 m0, s19
	v_mfma_f32_32x32x16_bf16 v[80:95], v[196:199], v[204:207], v[80:95]
	v_mfma_f32_32x32x16_bf16 v[16:31], v[196:199], v[208:211], v[16:31]
	v_mfma_f32_32x32x16_bf16 v[64:79], v[200:203], v[204:207], v[64:79]
	v_mfma_f32_32x32x16_bf16 v[0:15], v[200:203], v[208:211], v[0:15]
	v_add_u32_e32 v149, v212, v235
	v_add_u32_e32 v148, v213, v235
	ds_read_b128 v[188:191], v149
	ds_read_b128 v[192:195], v149 offset:4096
	ds_read_b128 v[196:199], v149 offset:8192
	ds_read_b128 v[200:203], v149 offset:12288
	ds_read_b128 v[204:207], v148 offset:32768
	ds_read_b128 v[208:211], v148 offset:36864
	s_add_i32 s17, s17, 0x8000
	v_lshl_add_u64 v[158:159], v[158:159], 0, s[10:11]
	s_cmp_eq_u32 s17, 0xf8000
	s_cbranch_scc0 .Lrot666_loop
; template <int EPI, int PN>
; __device__ void gemm_phase(const Params& p, const u16* __restrict__ A, const u16* __restrict__ Bt, int nNt, char* smem) {
;     ...
;     for (int kt = 0; kt < 32; ++kt) {
;       asm volatile("s_waitcnt vmcnt(0)" ::: "memory");
;       __builtin_amdgcn_s_barrier();
;       const u16* Ab = ring + (kt & 1) * STG;
;       const u16* Bb = Ab + 16384;
;       u16* st = ring + ((kt + 1) & 1) * STG;
;       const bool pre = (kt + 1 < 32);
;       s16x8 af[2][4], bf[2][2];
;       auto ldfrag = [&](int ks, int slot) {
; #pragma unroll
;         for (int i = 0; i < 4; ++i) {
;           const int row = wr * 128 + i * 32 + lr;
;           af[slot][i] = *(const s16x8*)(Ab + row * 64 + (((ks * 2 + lh) ^ ((row >> 1) & 7)) * 8));
;         }
; #pragma unroll
;         for (int j = 0; j < 2; ++j) {
;           const int rowb = nh * 128 + wc * 64 + j * 32 + lr;
;           bf[slot][j] = *(const s16x8*)(Bb + rowb * 64 + (((ks * 2 + lh) ^ ((rowb >> 1) & 7)) * 8));
;         }
;       };
;       ldfrag(0, 0);
;       ldfrag(1, 1);
;       __builtin_amdgcn_sched_barrier(0);
; #pragma unroll
;       for (int ks = 0; ks < 4; ++ks) {
;         const int slot = ks & 1;
; #pragma unroll
;         for (int i = 0; i < 4; ++i) {
;           acc[i][0] = mfma32(af[slot][i], bf[slot][0], acc[i][0]);
;           acc[i][1] = mfma32(af[slot][i], bf[slot][1], acc[i][1]);
;           __builtin_amdgcn_sched_barrier(0);
;           if (pre && (i & 1) == 0) {
;             const int pi = ks * 2 + (i >> 1);
;             if (pi < 4) glds16(Ag0 + (size_t)pi * 64 * LDK + (kt + 1) * 64, st + (srow + 64 * pi) * 64 + sch * 8);
;             else glds16(Bg0 + (size_t)(pi - 4) * 64 * LDK + (kt + 1) * 64, st + 16384 + (srow + 64 * (pi - 4)) * 64 + sch * 8);
;             __builtin_amdgcn_sched_barrier(0);
;           }
;         }
;         if (ks + 2 < 4) { ldfrag(ks + 2, slot); __builtin_amdgcn_sched_barrier(0); }
;       }
	s_add_i32 s18, s17, 0xffff8000
	s_and_b32 s18, s18, 0x8000
	s_lshl_b32 s18, s18, 1
	v_lshl_or_b32 v128, v143, 1, s18
	v_lshl_add_u32 v166, v147, 1, s18
	s_and_b32 s98, s17, 0x8000
	s_lshl_b32 s98, s98, 1
	s_waitcnt lgkmcnt(7)
	v_mfma_f32_32x32x16_bf16 v[112:127], v[162:165], v[180:183], v[112:127]
	v_add3_u32 v148, s98, v224, v156
	s_waitcnt lgkmcnt(6)
	v_mfma_f32_32x32x16_bf16 v[48:63], v[162:165], v[184:187], v[48:63]
	v_readfirstlane_b32 s100, v148
	s_mov_b32 s19, m0
	s_add_i32 m0, s100, 0x8000
	s_nop 0
	global_load_lds_dwordx4 v[160:161], off
	v_mfma_f32_32x32x16_bf16 v[96:111], v[168:171], v[180:183], v[96:111]
	v_lshl_add_u64 v[162:163], v[160:161], 0, s[4:5]
	s_add_i32 m0, s100, 0xa000
	s_nop 0
	global_load_lds_dwordx4 v[162:163], off
	v_mfma_f32_32x32x16_bf16 v[32:47], v[168:171], v[184:187], v[32:47]
	v_lshl_add_u64 v[164:165], v[160:161], 0, s[6:7]
	s_add_i32 m0, s100, 0xc000
	s_nop 0
	global_load_lds_dwordx4 v[164:165], off
	v_mfma_f32_32x32x16_bf16 v[80:95], v[172:175], v[180:183], v[80:95]
	v_lshl_add_u64 v[162:163], v[160:161], 0, s[8:9]
	s_add_i32 m0, s100, 0xe000
	s_nop 0
	global_load_lds_dwordx4 v[162:163], off
	s_mov_b32 m0, s19
	v_mfma_f32_32x32x16_bf16 v[16:31], v[172:175], v[184:187], v[16:31]
	v_mfma_f32_32x32x16_bf16 v[64:79], v[176:179], v[180:183], v[64:79]
	v_mfma_f32_32x32x16_bf16 v[0:15], v[176:179], v[184:187], v[0:15]
	v_lshl_add_u64 v[160:161], v[160:161], 0, s[10:11]
	v_add_u32_e32 v176, v128, v236
	ds_read_b128 v[162:165], v176
	ds_read_b128 v[168:171], v176 offset:4096
	ds_read_b128 v[172:175], v176 offset:8192
	ds_read_b128 v[176:179], v176 offset:12288
	v_add_u32_e32 v184, v166, v236
	ds_read_b128 v[180:183], v184 offset:32768
	ds_read_b128 v[184:187], v184 offset:36864
	s_waitcnt lgkmcnt(7)
	v_mfma_f32_32x32x16_bf16 v[112:127], v[188:191], v[204:207], v[112:127]
	s_waitcnt lgkmcnt(6)
	v_mfma_f32_32x32x16_bf16 v[48:63], v[188:191], v[208:211], v[48:63]
	v_mfma_f32_32x32x16_bf16 v[96:111], v[192:195], v[204:207], v[96:111]
	v_mfma_f32_32x32x16_bf16 v[32:47], v[192:195], v[208:211], v[32:47]
	v_mfma_f32_32x32x16_bf16 v[80:95], v[196:199], v[204:207], v[80:95]
	v_mfma_f32_32x32x16_bf16 v[16:31], v[196:199], v[208:211], v[16:31]
	v_mfma_f32_32x32x16_bf16 v[64:79], v[200:203], v[204:207], v[64:79]
	v_mfma_f32_32x32x16_bf16 v[0:15], v[200:203], v[208:211], v[0:15]
	v_add_u32_e32 v128, v128, v237
	ds_read_b128 v[188:191], v128
	ds_read_b128 v[192:195], v128 offset:4096
	ds_read_b128 v[196:199], v128 offset:8192
	ds_read_b128 v[200:203], v128 offset:12288
	v_add_u32_e32 v128, v166, v237
	ds_read_b128 v[204:207], v128 offset:32768
	ds_read_b128 v[208:211], v128 offset:36864
	s_waitcnt lgkmcnt(7)
	v_mfma_f32_32x32x16_bf16 v[112:127], v[162:165], v[180:183], v[112:127]
	s_waitcnt lgkmcnt(6)
	v_mfma_f32_32x32x16_bf16 v[48:63], v[162:165], v[184:187], v[48:63]
	v_mfma_f32_32x32x16_bf16 v[96:111], v[168:171], v[180:183], v[96:111]
	v_mfma_f32_32x32x16_bf16 v[32:47], v[168:171], v[184:187], v[32:47]
	v_mfma_f32_32x32x16_bf16 v[80:95], v[172:175], v[180:183], v[80:95]
	v_mfma_f32_32x32x16_bf16 v[16:31], v[172:175], v[184:187], v[16:31]
	v_mfma_f32_32x32x16_bf16 v[64:79], v[176:179], v[180:183], v[64:79]
	v_mfma_f32_32x32x16_bf16 v[0:15], v[176:179], v[184:187], v[0:15]
	s_waitcnt lgkmcnt(1)
	v_mfma_f32_32x32x16_bf16 v[112:127], v[188:191], v[204:207], v[112:127]
	s_waitcnt lgkmcnt(0)
	v_mfma_f32_32x32x16_bf16 v[48:63], v[188:191], v[208:211], v[48:63]
	v_mfma_f32_32x32x16_bf16 v[96:111], v[192:195], v[204:207], v[96:111]
	v_mfma_f32_32x32x16_bf16 v[32:47], v[192:195], v[208:211], v[32:47]
	v_mfma_f32_32x32x16_bf16 v[80:95], v[196:199], v[204:207], v[80:95]
	v_mfma_f32_32x32x16_bf16 v[16:31], v[196:199], v[208:211], v[16:31]
	v_mfma_f32_32x32x16_bf16 v[64:79], v[200:203], v[204:207], v[64:79]
	v_mfma_f32_32x32x16_bf16 v[0:15], v[200:203], v[208:211], v[0:15]
	s_waitcnt vmcnt(0)
	s_barrier
	ds_read_b128 v[158:161], v226
	ds_read_b128 v[162:165], v226 offset:4096
	ds_read_b128 v[168:171], v226 offset:8192
	ds_read_b128 v[172:175], v226 offset:12288
	ds_read_b128 v[176:179], v227
	ds_read_b128 v[180:183], v227 offset:4096
	ds_read_b128 v[184:187], v228
	ds_read_b128 v[188:191], v228 offset:4096
	ds_read_b128 v[192:195], v228 offset:8192
	ds_read_b128 v[196:199], v228 offset:12288
	ds_read_b128 v[200:203], v229
	ds_read_b128 v[204:207], v229 offset:4096
	s_waitcnt lgkmcnt(7)
	v_mfma_f32_32x32x16_bf16 v[112:127], v[158:161], v[176:179], v[112:127]
	s_waitcnt lgkmcnt(6)
	v_mfma_f32_32x32x16_bf16 v[48:63], v[158:161], v[180:183], v[48:63]
	v_mfma_f32_32x32x16_bf16 v[96:111], v[162:165], v[176:179], v[96:111]
	v_mfma_f32_32x32x16_bf16 v[32:47], v[162:165], v[180:183], v[32:47]
	v_mfma_f32_32x32x16_bf16 v[80:95], v[168:171], v[176:179], v[80:95]
	v_mfma_f32_32x32x16_bf16 v[16:31], v[168:171], v[180:183], v[16:31]
	v_mfma_f32_32x32x16_bf16 v[64:79], v[172:175], v[176:179], v[64:79]
	v_mfma_f32_32x32x16_bf16 v[0:15], v[172:175], v[180:183], v[0:15]
	ds_read_b128 v[158:161], v230
	ds_read_b128 v[162:165], v230 offset:4096
	ds_read_b128 v[168:171], v230 offset:8192
	ds_read_b128 v[172:175], v230 offset:12288
	ds_read_b128 v[176:179], v231
	ds_read_b128 v[180:183], v231 offset:4096
	s_waitcnt lgkmcnt(7)
	v_mfma_f32_32x32x16_bf16 v[112:127], v[184:187], v[200:203], v[112:127]
	s_waitcnt lgkmcnt(6)
; __device__ __forceinline__ int accrow(int reg, int lh) { return (reg & 3) + 8 * (reg >> 2) + 4 * lh; }
; template <int EPI, int PN>
; __device__ void gemm_phase(const Params& p, const u16* __restrict__ A, const u16* __restrict__ Bt, int nNt, char* smem) {
;     ...
;       for (int ks = 0; ks < 4; ++ks) {
;         const int slot = ks & 1;
; #pragma unroll
;         for (int i = 0; i < 4; ++i) {
;           acc[i][0] = mfma32(af[slot][i], bf[slot][0], acc[i][0]);
;           acc[i][1] = mfma32(af[slot][i], bf[slot][1], acc[i][1]);
;     ...
;     __syncthreads();
;     int mte = __builtin_amdgcn_readfirstlane(mt), nte = __builtin_amdgcn_readfirstlane(nt), lrE = lr, lhE = lh, laneE = lane;
;     asm volatile("" : "+s"(mte), "+s"(nte), "+v"(lrE), "+v"(lhE), "+v"(laneE));
;     unsigned char* et = (unsigned char*)smem + wv * 18432;
;     const int col0 = nte * 256 + nh * 128 + wc * 64;
;     const size_t row0 = (size_t)mte * 256 + wr * 128;
;     if (EPI == 1) {
; #pragma unroll
;       for (int j = 0; j < 2; ++j) {
; #pragma unroll
;         for (int i = 0; i < 4; ++i)
; #pragma unroll
;           for (int r = 0; r < 16; ++r) *(float*)(et + (i * 32 + accrow(r, lhE)) * 144 + lrE * 4) = acc[i][j][r];
; #pragma unroll
;         for (int it = 0; it < 16; ++it) {
;           const int c = it * 64 + laneE, row = c >> 3, seg = c & 7;
;           const float4 v = *(const float4*)(et + row * 144 + seg * 16);
;           const size_t g = (row0 + row) * DM + col0 + j * 32 + seg * 4;
;           const float4 xv = *(const float4*)(p.x + g);
;           const float4 hv = make_float4(xv.x + v.x, xv.y + v.y, xv.z + v.z, xv.w + v.w);
;           *(float4*)(p.out + g) = hv;
	v_mfma_f32_32x32x16_bf16 v[48:63], v[184:187], v[204:207], v[48:63]
	v_mfma_f32_32x32x16_bf16 v[96:111], v[188:191], v[200:203], v[96:111]
	v_mfma_f32_32x32x16_bf16 v[32:47], v[188:191], v[204:207], v[32:47]
	v_mfma_f32_32x32x16_bf16 v[80:95], v[192:195], v[200:203], v[80:95]
	v_mfma_f32_32x32x16_bf16 v[16:31], v[192:195], v[204:207], v[16:31]
	v_mfma_f32_32x32x16_bf16 v[64:79], v[196:199], v[200:203], v[64:79]
	v_mfma_f32_32x32x16_bf16 v[0:15], v[196:199], v[204:207], v[0:15]
	ds_read_b128 v[184:187], v232
	ds_read_b128 v[188:191], v232 offset:4096
	ds_read_b128 v[192:195], v232 offset:8192
	ds_read_b128 v[196:199], v232 offset:12288
	ds_read_b128 v[200:203], v233
	ds_read_b128 v[204:207], v233 offset:4096
	s_waitcnt lgkmcnt(7)
	v_mfma_f32_32x32x16_bf16 v[112:127], v[158:161], v[176:179], v[112:127]
	s_waitcnt lgkmcnt(6)
	v_mfma_f32_32x32x16_bf16 v[48:63], v[158:161], v[180:183], v[48:63]
	v_mfma_f32_32x32x16_bf16 v[96:111], v[162:165], v[176:179], v[96:111]
	v_mfma_f32_32x32x16_bf16 v[32:47], v[162:165], v[180:183], v[32:47]
	v_mfma_f32_32x32x16_bf16 v[80:95], v[168:171], v[176:179], v[80:95]
	v_mfma_f32_32x32x16_bf16 v[16:31], v[168:171], v[180:183], v[16:31]
	v_mfma_f32_32x32x16_bf16 v[64:79], v[172:175], v[176:179], v[64:79]
	v_mfma_f32_32x32x16_bf16 v[0:15], v[172:175], v[180:183], v[0:15]
	s_waitcnt lgkmcnt(1)
	v_mfma_f32_32x32x16_bf16 v[112:127], v[184:187], v[200:203], v[112:127]
	s_waitcnt lgkmcnt(0)
	v_mfma_f32_32x32x16_bf16 v[48:63], v[184:187], v[204:207], v[48:63]
	v_mfma_f32_32x32x16_bf16 v[96:111], v[188:191], v[200:203], v[96:111]
	v_mfma_f32_32x32x16_bf16 v[32:47], v[188:191], v[204:207], v[32:47]
	v_mfma_f32_32x32x16_bf16 v[80:95], v[192:195], v[200:203], v[80:95]
	v_mfma_f32_32x32x16_bf16 v[16:31], v[192:195], v[204:207], v[16:31]
	v_mfma_f32_32x32x16_bf16 v[64:79], v[196:199], v[200:203], v[64:79]
	v_mfma_f32_32x32x16_bf16 v[0:15], v[196:199], v[204:207], v[0:15]
	v_mov_b32_e32 v128, v139
	v_mov_b32_e32 v148, v137
	v_mov_b32_e32 v218, v135
	s_barrier
	v_readlane_b32 s52, v253, 7
	v_lshl_add_u32 v172, s13, 8, v145
	s_ashr_i32 s13, s12, 31
	s_lshl_b64 s[12:13], s[12:13], 8
	v_ashrrev_i32_e32 v158, 3, v218
	v_mov_b32_e32 v163, s13
	v_or_b32_e32 v162, s12, v134
	v_ashrrev_i32_e32 v159, 31, v158
	v_and_b32_e32 v149, 7, v218
	v_ashrrev_i32_e32 v173, 31, v172
	v_lshl_add_u64 v[174:175], v[162:163], 0, v[158:159]
	v_lshl_or_b32 v164, v149, 2, v172
	v_mov_b32_e32 v165, v173
	v_lshlrev_b64 v[160:161], 11, v[174:175]
	v_lshl_add_u64 v[160:161], v[160:161], 0, v[164:165]
	v_lshlrev_b64 v[176:177], 2, v[160:161]
	v_readlane_b32 s53, v253, 8
	v_lshl_add_u32 v166, v149, 4, v225
	v_lshlrev_b32_e32 v148, 2, v148
	v_lshl_add_u64 v[160:161], s[52:53], 0, v[176:177]
	global_load_dwordx4 v[168:171], v[160:161], off
	v_mad_u64_u32 v[158:159], s[12:13], v158, s14, v[166:167]
	v_mul_lo_u32 v128, v128, s15
	v_add3_u32 v159, v225, v148, v128
	ds_write_b32 v159, v112
	ds_write_b32 v159, v113 offset:144
	ds_write_b32 v159, v114 offset:288
	ds_write_b32 v159, v115 offset:432
	ds_write_b32 v159, v116 offset:1152
	ds_write_b32 v159, v117 offset:1296
	ds_write_b32 v159, v118 offset:1440
	ds_write_b32 v159, v119 offset:1584
	ds_write_b32 v159, v120 offset:2304
	ds_write_b32 v159, v121 offset:2448
	ds_write_b32 v159, v122 offset:2592
	ds_write_b32 v159, v123 offset:2736
	ds_write_b32 v159, v124 offset:3456
	ds_write_b32 v159, v125 offset:3600
	ds_write_b32 v159, v126 offset:3744
	ds_write_b32 v159, v127 offset:3888
	ds_write_b32 v159, v96 offset:4608
	ds_write_b32 v159, v97 offset:4752
	ds_write_b32 v159, v98 offset:4896
	ds_write_b32 v159, v99 offset:5040
	ds_write_b32 v159, v100 offset:5760
	ds_write_b32 v159, v101 offset:5904
	ds_write_b32 v159, v102 offset:6048
	ds_write_b32 v159, v103 offset:6192
	ds_write_b32 v159, v104 offset:6912
	ds_write_b32 v159, v105 offset:7056
	ds_write_b32 v159, v106 offset:7200
	ds_write_b32 v159, v107 offset:7344
	ds_write_b32 v159, v108 offset:8064
	ds_write_b32 v159, v109 offset:8208
	ds_write_b32 v159, v110 offset:8352
	ds_write_b32 v159, v111 offset:8496
	ds_write_b32 v159, v80 offset:9216
	ds_write_b32 v159, v81 offset:9360
	ds_write_b32 v159, v82 offset:9504
	ds_write_b32 v159, v83 offset:9648
	ds_write_b32 v159, v84 offset:10368
	ds_write_b32 v159, v85 offset:10512
	ds_write_b32 v159, v86 offset:10656
	ds_write_b32 v159, v87 offset:10800
	ds_write_b32 v159, v88 offset:11520
	ds_write_b32 v159, v89 offset:11664
	ds_write_b32 v159, v90 offset:11808
	ds_write_b32 v159, v91 offset:11952
	ds_write_b32 v159, v92 offset:12672
	ds_write_b32 v159, v93 offset:12816
	ds_write_b32 v159, v94 offset:12960
	ds_write_b32 v159, v95 offset:13104
	ds_write_b32 v159, v64 offset:13824
	ds_write_b32 v159, v65 offset:13968
	ds_write_b32 v159, v66 offset:14112
	ds_write_b32 v159, v67 offset:14256
	ds_write_b32 v159, v68 offset:14976
	ds_write_b32 v159, v69 offset:15120
	ds_write_b32 v159, v70 offset:15264
	ds_write_b32 v159, v71 offset:15408
	ds_write_b32 v159, v72 offset:16128
	ds_write_b32 v159, v73 offset:16272
	ds_write_b32 v159, v74 offset:16416
	ds_write_b32 v159, v75 offset:16560
	ds_write_b32 v159, v76 offset:17280
	ds_write_b32 v159, v77 offset:17424
	ds_write_b32 v159, v78 offset:17568
	ds_write_b32 v159, v79 offset:17712
	ds_read_b128 v[66:69], v158
	v_readlane_b32 s36, v253, 23
	v_readlane_b32 s40, v253, 27
	v_readlane_b32 s41, v253, 28
	v_readlane_b32 s42, v253, 29
	v_readlane_b32 s43, v253, 30
	s_mov_b64 s[20:21], s[40:41]
	s_mov_b64 s[22:23], s[42:43]
	v_lshl_add_u64 v[64:65], s[20:21], 0, v[176:177]
	v_mov_b64_e32 v[102:103], s[22:23]
	v_lshlrev_b64 v[104:105], 1, v[172:173]
	v_lshlrev_b32_e32 v128, 3, v149
	v_readlane_b32 s54, v253, 9
	v_readlane_b32 s55, v253, 10
	v_readlane_b32 s56, v253, 11
	v_readlane_b32 s57, v253, 12
	v_readlane_b32 s58, v253, 13
	v_readlane_b32 s59, v253, 14
	v_readlane_b32 s60, v253, 15
	v_readlane_b32 s61, v253, 16
	v_readlane_b32 s62, v253, 17
	v_readlane_b32 s63, v253, 18
	v_readlane_b32 s64, v253, 19
	v_readlane_b32 s65, v253, 20
	v_readlane_b32 s66, v253, 21
	v_readlane_b32 s67, v253, 22
	v_readlane_b32 s37, v253, 24
	v_readlane_b32 s38, v253, 25
	v_readlane_b32 s39, v253, 26
	v_readlane_b32 s44, v253, 31
	v_readlane_b32 s45, v253, 32
	v_readlane_b32 s46, v253, 33
	v_readlane_b32 s47, v253, 34
	v_readlane_b32 s48, v253, 35
	v_readlane_b32 s49, v253, 36
	v_readlane_b32 s50, v253, 37
	v_readlane_b32 s51, v253, 38
	s_waitcnt vmcnt(0) lgkmcnt(0)
; template <int EPI, int PN>
; __device__ void gemm_phase(const Params& p, const u16* __restrict__ A, const u16* __restrict__ Bt, int nNt, char* smem) {
;     ...
;         for (int it = 0; it < 16; ++it) {
;           const int c = it * 64 + laneE, row = c >> 3, seg = c & 7;
;           const float4 v = *(const float4*)(et + row * 144 + seg * 16);
;           const size_t g = (row0 + row) * DM + col0 + j * 32 + seg * 4;
;           const float4 xv = *(const float4*)(p.x + g);
;           const float4 hv = make_float4(xv.x + v.x, xv.y + v.y, xv.z + v.z, xv.w + v.w);
;           *(float4*)(p.out + g) = hv;
;           uint2 hb; hb.x = pack2(hv.x, hv.y); hb.y = pack2(hv.z, hv.w);
;           *(uint2*)(p.xn + (row0 + row) * LDK + col0 + j * 32 + seg * 4) = hb;
;         }
	v_pk_add_f32 v[66:67], v[66:67], v[168:169]
	v_pk_add_f32 v[68:69], v[68:69], v[170:171]
	global_store_dwordx4 v[64:65], v[66:69], off
	v_cvt_pk_bf16_f32 v70, v66, v67
	v_cvt_pk_bf16_f32 v71, v68, v69
	v_mad_u64_u32 v[66:67], s[12:13], v174, s2, v[102:103]
	v_mad_i32_i24 v67, v175, s2, v67
	v_lshl_add_u64 v[66:67], v[66:67], 0, v[104:105]
	v_lshl_add_u64 v[66:67], v[66:67], 0, v[128:129]
	v_add_u32_e32 v68, 64, v218
	global_store_dwordx2 v[66:67], v[70:71], off
	v_ashrrev_i32_e32 v70, 3, v68
	v_ashrrev_i32_e32 v71, 31, v70
	v_lshl_add_u64 v[74:75], v[162:163], 0, v[70:71]
	v_lshlrev_b64 v[68:69], 11, v[74:75]
	v_lshl_add_u64 v[68:69], v[68:69], 0, v[164:165]
	v_lshlrev_b64 v[76:77], 2, v[68:69]
	v_lshl_add_u64 v[68:69], s[52:53], 0, v[76:77]
	global_load_dwordx4 v[78:81], v[68:69], off
	v_mad_u64_u32 v[72:73], s[12:13], v70, s14, v[166:167]
	v_add_u32_e32 v71, 0x80, v218
	ds_read_b128 v[82:85], v72
	v_ashrrev_i32_e32 v90, 3, v71
	v_ashrrev_i32_e32 v91, 31, v90
	v_lshl_add_u64 v[94:95], v[162:163], 0, v[90:91]
	v_mad_u64_u32 v[70:71], s[12:13], v74, s2, v[102:103]
	v_lshlrev_b64 v[86:87], 11, v[94:95]
	v_mad_i32_i24 v71, v75, s2, v71
	v_lshl_add_u64 v[74:75], v[86:87], 0, v[164:165]
	v_lshl_add_u64 v[70:71], v[70:71], 0, v[104:105]
	v_lshl_add_u64 v[76:77], s[20:21], 0, v[76:77]
	v_lshlrev_b64 v[96:97], 2, v[74:75]
	v_lshl_add_u64 v[74:75], v[70:71], 0, v[128:129]
	v_lshl_add_u64 v[70:71], s[52:53], 0, v[96:97]
	v_add_u32_e32 v73, 0xc0, v218
	v_ashrrev_i32_e32 v98, 3, v73
	v_ashrrev_i32_e32 v99, 31, v98
	v_lshl_add_u64 v[106:107], v[162:163], 0, v[98:99]
	v_add_u32_e32 v73, 0x100, v218
	v_ashrrev_i32_e32 v110, 3, v73
	v_ashrrev_i32_e32 v111, 31, v110
	v_lshl_add_u64 v[114:115], v[162:163], 0, v[110:111]
	v_add_u32_e32 v73, 0x140, v218
	v_ashrrev_i32_e32 v118, 3, v73
	v_ashrrev_i32_e32 v119, 31, v118
	v_lshl_add_u64 v[122:123], v[162:163], 0, v[118:119]
	v_add_u32_e32 v73, 0x180, v218
	v_ashrrev_i32_e32 v126, 3, v73
	v_ashrrev_i32_e32 v127, 31, v126
	v_lshl_add_u64 v[172:173], v[162:163], 0, v[126:127]
	v_add_u32_e32 v73, 0x1c0, v218
	v_ashrrev_i32_e32 v176, 3, v73
	v_ashrrev_i32_e32 v177, 31, v176
	v_add_u32_e32 v73, 0x200, v218
	v_ashrrev_i32_e32 v182, 3, v73
	v_ashrrev_i32_e32 v183, 31, v182
	v_lshl_add_u64 v[186:187], v[162:163], 0, v[182:183]
	v_add_u32_e32 v73, 0x240, v218
	v_ashrrev_i32_e32 v190, 3, v73
	v_ashrrev_i32_e32 v191, 31, v190
	v_lshl_add_u64 v[194:195], v[162:163], 0, v[190:191]
	v_add_u32_e32 v73, 0x280, v218
	v_ashrrev_i32_e32 v198, 3, v73
	v_ashrrev_i32_e32 v199, 31, v198
	v_lshl_add_u64 v[202:203], v[162:163], 0, v[198:199]
	v_add_u32_e32 v73, 0x2c0, v218
	v_ashrrev_i32_e32 v206, 3, v73
	v_ashrrev_i32_e32 v207, 31, v206
	v_lshl_add_u64 v[210:211], v[162:163], 0, v[206:207]
	v_add_u32_e32 v73, 0x300, v218
	v_ashrrev_i32_e32 v214, 3, v73
	v_ashrrev_i32_e32 v215, 31, v214
	v_lshl_add_u64 v[220:221], v[162:163], 0, v[214:215]
	v_add_u32_e32 v73, 0x340, v218
	v_ashrrev_i32_e32 v238, 3, v73
	v_ashrrev_i32_e32 v239, 31, v238
	v_lshl_add_u64 v[242:243], v[162:163], 0, v[238:239]
	v_add_u32_e32 v73, 0x380, v218
	v_ashrrev_i32_e32 v246, 3, v73
	v_ashrrev_i32_e32 v247, 31, v246
	v_lshl_add_u64 v[248:249], v[162:163], 0, v[246:247]
	v_add_u32_e32 v73, 0x3c0, v218
	v_mad_u64_u32 v[218:219], s[12:13], v246, s14, v[166:167]
	v_ashrrev_i32_e32 v148, 3, v73
	v_ashrrev_i32_e32 v149, 31, v148
	v_lshl_add_u64 v[246:247], v[162:163], 0, v[148:149]
	s_waitcnt vmcnt(0) lgkmcnt(0)
	v_pk_add_f32 v[78:79], v[82:83], v[78:79]
	v_pk_add_f32 v[80:81], v[84:85], v[80:81]
	global_store_dwordx4 v[76:77], v[78:81], off
	v_lshlrev_b64 v[82:83], 11, v[106:107]
	v_lshl_add_u64 v[82:83], v[82:83], 0, v[164:165]
	v_cvt_pk_bf16_f32 v78, v78, v79
	v_cvt_pk_bf16_f32 v79, v80, v81
	global_store_dwordx2 v[74:75], v[78:79], off
	global_load_dwordx4 v[86:89], v[70:71], off
	v_mad_u64_u32 v[80:81], s[12:13], v90, s14, v[166:167]
	ds_read_b128 v[90:93], v80
	v_mad_u64_u32 v[78:79], s[12:13], v94, s2, v[102:103]
	v_mad_i32_i24 v79, v95, s2, v79
	v_lshl_add_u64 v[78:79], v[78:79], 0, v[104:105]
	v_lshl_add_u64 v[84:85], s[20:21], 0, v[96:97]
	v_lshlrev_b64 v[108:109], 2, v[82:83]
	v_lshl_add_u64 v[82:83], v[78:79], 0, v[128:129]
	v_lshl_add_u64 v[78:79], s[52:53], 0, v[108:109]
	s_waitcnt vmcnt(0) lgkmcnt(0)
	v_pk_add_f32 v[86:87], v[90:91], v[86:87]
	v_pk_add_f32 v[88:89], v[92:93], v[88:89]
	global_store_dwordx4 v[84:85], v[86:89], off
	v_lshlrev_b64 v[90:91], 11, v[114:115]
	v_lshl_add_u64 v[90:91], v[90:91], 0, v[164:165]
	v_cvt_pk_bf16_f32 v86, v86, v87
	v_cvt_pk_bf16_f32 v87, v88, v89
	global_store_dwordx2 v[82:83], v[86:87], off
	global_load_dwordx4 v[94:97], v[78:79], off
	v_mad_u64_u32 v[88:89], s[12:13], v98, s14, v[166:167]
	ds_read_b128 v[98:101], v88
	v_mad_u64_u32 v[86:87], s[12:13], v106, s2, v[102:103]
	v_mad_i32_i24 v87, v107, s2, v87
	v_lshl_add_u64 v[86:87], v[86:87], 0, v[104:105]
	v_lshl_add_u64 v[92:93], s[20:21], 0, v[108:109]
	v_lshlrev_b64 v[116:117], 2, v[90:91]
	v_lshl_add_u64 v[90:91], v[86:87], 0, v[128:129]
	v_lshl_add_u64 v[86:87], s[52:53], 0, v[116:117]
	s_waitcnt vmcnt(0) lgkmcnt(0)
	v_pk_add_f32 v[94:95], v[98:99], v[94:95]
	v_pk_add_f32 v[96:97], v[100:101], v[96:97]
	global_store_dwordx4 v[92:93], v[94:97], off
	v_lshlrev_b64 v[98:99], 11, v[122:123]
	v_lshl_add_u64 v[98:99], v[98:99], 0, v[164:165]
	v_cvt_pk_bf16_f32 v94, v94, v95
	v_cvt_pk_bf16_f32 v95, v96, v97
	global_store_dwordx2 v[90:91], v[94:95], off
	global_load_dwordx4 v[106:109], v[86:87], off
	v_mad_u64_u32 v[96:97], s[12:13], v110, s14, v[166:167]
	ds_read_b128 v[110:113], v96
	v_mad_u64_u32 v[94:95], s[12:13], v114, s2, v[102:103]
	v_mad_i32_i24 v95, v115, s2, v95
	v_lshl_add_u64 v[94:95], v[94:95], 0, v[104:105]
	v_lshl_add_u64 v[100:101], s[20:21], 0, v[116:117]
	v_lshlrev_b64 v[124:125], 2, v[98:99]
	v_lshl_add_u64 v[98:99], v[94:95], 0, v[128:129]
	v_lshl_add_u64 v[94:95], s[52:53], 0, v[124:125]
	s_waitcnt vmcnt(0) lgkmcnt(0)
; template <int EPI, int PN>
; __device__ void gemm_phase(const Params& p, const u16* __restrict__ A, const u16* __restrict__ Bt, int nNt, char* smem) {
;     ...
;         for (int it = 0; it < 16; ++it) {
;           const int c = it * 64 + laneE, row = c >> 3, seg = c & 7;
;           const float4 v = *(const float4*)(et + row * 144 + seg * 16);
;           const size_t g = (row0 + row) * DM + col0 + j * 32 + seg * 4;
;           const float4 xv = *(const float4*)(p.x + g);
;           const float4 hv = make_float4(xv.x + v.x, xv.y + v.y, xv.z + v.z, xv.w + v.w);
;           *(float4*)(p.out + g) = hv;
;           uint2 hb; hb.x = pack2(hv.x, hv.y); hb.y = pack2(hv.z, hv.w);
;           *(uint2*)(p.xn + (row0 + row) * LDK + col0 + j * 32 + seg * 4) = hb;
;         }
	v_pk_add_f32 v[106:107], v[110:111], v[106:107]
	v_pk_add_f32 v[108:109], v[112:113], v[108:109]
	global_store_dwordx4 v[100:101], v[106:109], off
	v_lshlrev_b64 v[110:111], 11, v[172:173]
	v_lshl_add_u64 v[110:111], v[110:111], 0, v[164:165]
	v_cvt_pk_bf16_f32 v106, v106, v107
	v_cvt_pk_bf16_f32 v107, v108, v109
	global_store_dwordx2 v[98:99], v[106:107], off
	global_load_dwordx4 v[114:117], v[94:95], off
	v_mad_u64_u32 v[108:109], s[12:13], v118, s14, v[166:167]
	ds_read_b128 v[118:121], v108
	v_mad_u64_u32 v[106:107], s[12:13], v122, s2, v[102:103]
	v_mad_i32_i24 v107, v123, s2, v107
	v_lshl_add_u64 v[106:107], v[106:107], 0, v[104:105]
	v_lshl_add_u64 v[112:113], s[20:21], 0, v[124:125]
	v_lshlrev_b64 v[174:175], 2, v[110:111]
	v_lshl_add_u64 v[110:111], v[106:107], 0, v[128:129]
	v_lshl_add_u64 v[106:107], s[52:53], 0, v[174:175]
	s_waitcnt vmcnt(0) lgkmcnt(0)
	v_pk_add_f32 v[114:115], v[118:119], v[114:115]
	v_pk_add_f32 v[116:117], v[120:121], v[116:117]
	global_store_dwordx4 v[112:113], v[114:117], off
	v_lshl_add_u64 v[120:121], s[20:21], 0, v[174:175]
	s_nop 0
	v_cvt_pk_bf16_f32 v114, v114, v115
	v_cvt_pk_bf16_f32 v115, v116, v117
	global_store_dwordx2 v[110:111], v[114:115], off
	global_load_dwordx4 v[122:125], v[106:107], off
	v_mad_u64_u32 v[116:117], s[12:13], v126, s14, v[166:167]
	ds_read_b128 v[168:171], v116
	v_lshl_add_u64 v[126:127], v[162:163], 0, v[176:177]
	v_mad_u64_u32 v[114:115], s[12:13], v172, s2, v[102:103]
	v_lshlrev_b64 v[118:119], 11, v[126:127]
	v_mad_i32_i24 v115, v173, s2, v115
	v_lshl_add_u64 v[118:119], v[118:119], 0, v[164:165]
	v_lshl_add_u64 v[114:115], v[114:115], 0, v[104:105]
	v_lshlrev_b64 v[178:179], 2, v[118:119]
	v_lshl_add_u64 v[118:119], v[114:115], 0, v[128:129]
	v_lshl_add_u64 v[114:115], s[52:53], 0, v[178:179]
	v_mad_u64_u32 v[162:163], s[12:13], v248, s2, v[102:103]
	v_mad_i32_i24 v163, v249, s2, v163
	v_lshl_add_u64 v[162:163], v[162:163], 0, v[104:105]
	s_waitcnt vmcnt(0) lgkmcnt(0)
	v_pk_add_f32 v[122:123], v[168:169], v[122:123]
	v_pk_add_f32 v[124:125], v[170:171], v[124:125]
	global_store_dwordx4 v[120:121], v[122:125], off
	v_lshlrev_b64 v[168:169], 11, v[186:187]
	s_nop 0
	v_cvt_pk_bf16_f32 v122, v122, v123
	v_cvt_pk_bf16_f32 v123, v124, v125
	global_store_dwordx2 v[118:119], v[122:123], off
	global_load_dwordx4 v[170:173], v[114:115], off
	v_mad_u64_u32 v[124:125], s[12:13], v176, s14, v[166:167]
	ds_read_b128 v[174:177], v124
	v_mad_u64_u32 v[122:123], s[12:13], v126, s2, v[102:103]
	v_mad_i32_i24 v123, v127, s2, v123
	v_lshl_add_u64 v[126:127], v[168:169], 0, v[164:165]
	v_lshl_add_u64 v[122:123], v[122:123], 0, v[104:105]
	v_lshl_add_u64 v[168:169], s[20:21], 0, v[178:179]
	v_lshlrev_b64 v[188:189], 2, v[126:127]
	v_lshl_add_u64 v[126:127], v[122:123], 0, v[128:129]
	v_lshl_add_u64 v[122:123], s[52:53], 0, v[188:189]
	s_waitcnt vmcnt(0) lgkmcnt(0)
	v_pk_add_f32 v[170:171], v[174:175], v[170:171]
	v_pk_add_f32 v[172:173], v[176:177], v[172:173]
	global_store_dwordx4 v[168:169], v[170:173], off
	v_lshlrev_b64 v[174:175], 11, v[194:195]
	v_lshl_add_u64 v[174:175], v[174:175], 0, v[164:165]
	v_cvt_pk_bf16_f32 v170, v170, v171
	v_cvt_pk_bf16_f32 v171, v172, v173
	global_store_dwordx2 v[126:127], v[170:171], off
	global_load_dwordx4 v[178:181], v[122:123], off
	v_mad_u64_u32 v[172:173], s[12:13], v182, s14, v[166:167]
	ds_read_b128 v[182:185], v172
	v_mad_u64_u32 v[170:171], s[12:13], v186, s2, v[102:103]
	v_mad_i32_i24 v171, v187, s2, v171
	v_lshl_add_u64 v[170:171], v[170:171], 0, v[104:105]
	v_lshl_add_u64 v[176:177], s[20:21], 0, v[188:189]
	v_lshlrev_b64 v[196:197], 2, v[174:175]
	v_lshl_add_u64 v[174:175], v[170:171], 0, v[128:129]
	v_lshl_add_u64 v[170:171], s[52:53], 0, v[196:197]
	s_waitcnt vmcnt(0) lgkmcnt(0)
	v_pk_add_f32 v[178:179], v[182:183], v[178:179]
	v_pk_add_f32 v[180:181], v[184:185], v[180:181]
	global_store_dwordx4 v[176:177], v[178:181], off
	v_lshlrev_b64 v[182:183], 11, v[202:203]
	v_lshl_add_u64 v[182:183], v[182:183], 0, v[164:165]
	v_cvt_pk_bf16_f32 v178, v178, v179
	v_cvt_pk_bf16_f32 v179, v180, v181
	global_store_dwordx2 v[174:175], v[178:179], off
	global_load_dwordx4 v[186:189], v[170:171], off
	v_mad_u64_u32 v[180:181], s[12:13], v190, s14, v[166:167]
	ds_read_b128 v[190:193], v180
	v_mad_u64_u32 v[178:179], s[12:13], v194, s2, v[102:103]
	v_mad_i32_i24 v179, v195, s2, v179
	v_lshl_add_u64 v[178:179], v[178:179], 0, v[104:105]
	v_lshl_add_u64 v[184:185], s[20:21], 0, v[196:197]
	v_lshlrev_b64 v[204:205], 2, v[182:183]
	v_lshl_add_u64 v[182:183], v[178:179], 0, v[128:129]
	v_lshl_add_u64 v[178:179], s[52:53], 0, v[204:205]
	s_waitcnt vmcnt(0) lgkmcnt(0)
	v_pk_add_f32 v[186:187], v[190:191], v[186:187]
	v_pk_add_f32 v[188:189], v[192:193], v[188:189]
	global_store_dwordx4 v[184:185], v[186:189], off
	v_lshlrev_b64 v[190:191], 11, v[210:211]
	v_lshl_add_u64 v[190:191], v[190:191], 0, v[164:165]
	v_cvt_pk_bf16_f32 v186, v186, v187
	v_cvt_pk_bf16_f32 v187, v188, v189
	global_store_dwordx2 v[182:183], v[186:187], off
	global_load_dwordx4 v[194:197], v[178:179], off
	v_mad_u64_u32 v[188:189], s[12:13], v198, s14, v[166:167]
	ds_read_b128 v[198:201], v188
	v_mad_u64_u32 v[186:187], s[12:13], v202, s2, v[102:103]
	v_mad_i32_i24 v187, v203, s2, v187
	v_lshl_add_u64 v[186:187], v[186:187], 0, v[104:105]
	v_lshl_add_u64 v[192:193], s[20:21], 0, v[204:205]
	v_lshlrev_b64 v[212:213], 2, v[190:191]
	v_lshl_add_u64 v[190:191], v[186:187], 0, v[128:129]
	v_lshl_add_u64 v[186:187], s[52:53], 0, v[212:213]
	s_waitcnt vmcnt(0) lgkmcnt(0)
; template <int EPI, int PN>
; __device__ void gemm_phase(const Params& p, const u16* __restrict__ A, const u16* __restrict__ Bt, int nNt, char* smem) {
;     ...
;   for (int q = jb;; q += NJ) {
;     const int pl = q / (4 * PN), w = q % (4 * PN);
;     const int gp = pl * 8 + xcd;
;     if (gp >= npatch) break;
;     ...
;         for (int it = 0; it < 16; ++it) {
;           const int c = it * 64 + laneE, row = c >> 3, seg = c & 7;
;           const float4 v = *(const float4*)(et + row * 144 + seg * 16);
;           const size_t g = (row0 + row) * DM + col0 + j * 32 + seg * 4;
;           const float4 xv = *(const float4*)(p.x + g);
;           const float4 hv = make_float4(xv.x + v.x, xv.y + v.y, xv.z + v.z, xv.w + v.w);
;           *(float4*)(p.out + g) = hv;
;           uint2 hb; hb.x = pack2(hv.x, hv.y); hb.y = pack2(hv.z, hv.w);
;           *(uint2*)(p.xn + (row0 + row) * LDK + col0 + j * 32 + seg * 4) = hb;
;         }
	v_pk_add_f32 v[194:195], v[198:199], v[194:195]
	v_pk_add_f32 v[196:197], v[200:201], v[196:197]
	global_store_dwordx4 v[192:193], v[194:197], off
	v_lshlrev_b64 v[198:199], 11, v[220:221]
	v_lshl_add_u64 v[198:199], v[198:199], 0, v[164:165]
	v_cvt_pk_bf16_f32 v194, v194, v195
	v_cvt_pk_bf16_f32 v195, v196, v197
	global_store_dwordx2 v[190:191], v[194:195], off
	global_load_dwordx4 v[202:205], v[186:187], off
	v_mad_u64_u32 v[196:197], s[12:13], v206, s14, v[166:167]
	ds_read_b128 v[206:209], v196
	v_mad_u64_u32 v[194:195], s[12:13], v210, s2, v[102:103]
	v_mad_i32_i24 v195, v211, s2, v195
	v_lshl_add_u64 v[194:195], v[194:195], 0, v[104:105]
	v_lshl_add_u64 v[200:201], s[20:21], 0, v[212:213]
	v_lshlrev_b64 v[222:223], 2, v[198:199]
	v_lshl_add_u64 v[198:199], v[194:195], 0, v[128:129]
	v_lshl_add_u64 v[194:195], s[52:53], 0, v[222:223]
	s_waitcnt vmcnt(0) lgkmcnt(0)
	v_pk_add_f32 v[202:203], v[206:207], v[202:203]
	v_pk_add_f32 v[204:205], v[208:209], v[204:205]
	global_store_dwordx4 v[200:201], v[202:205], off
	v_lshlrev_b64 v[206:207], 11, v[242:243]
	v_lshl_add_u64 v[206:207], v[206:207], 0, v[164:165]
	v_cvt_pk_bf16_f32 v202, v202, v203
	v_cvt_pk_bf16_f32 v203, v204, v205
	global_store_dwordx2 v[198:199], v[202:203], off
	global_load_dwordx4 v[210:213], v[194:195], off
	v_mad_u64_u32 v[204:205], s[12:13], v214, s14, v[166:167]
	ds_read_b128 v[214:217], v204
	v_mad_u64_u32 v[202:203], s[12:13], v220, s2, v[102:103]
	v_mad_i32_i24 v203, v221, s2, v203
	v_lshl_add_u64 v[202:203], v[202:203], 0, v[104:105]
	v_lshl_add_u64 v[208:209], s[20:21], 0, v[222:223]
	v_lshlrev_b64 v[244:245], 2, v[206:207]
	v_lshl_add_u64 v[206:207], v[202:203], 0, v[128:129]
	v_lshl_add_u64 v[202:203], s[52:53], 0, v[244:245]
	s_waitcnt vmcnt(0) lgkmcnt(0)
	v_pk_add_f32 v[210:211], v[214:215], v[210:211]
	v_pk_add_f32 v[212:213], v[216:217], v[212:213]
	global_store_dwordx4 v[208:209], v[210:213], off
	v_lshlrev_b64 v[214:215], 11, v[248:249]
	v_lshl_add_u64 v[214:215], v[214:215], 0, v[164:165]
	v_cvt_pk_bf16_f32 v210, v210, v211
	v_cvt_pk_bf16_f32 v211, v212, v213
	global_store_dwordx2 v[206:207], v[210:211], off
	global_load_dwordx4 v[220:223], v[202:203], off
	v_mad_u64_u32 v[212:213], s[12:13], v238, s14, v[166:167]
	ds_read_b128 v[238:241], v212
	v_mad_u64_u32 v[210:211], s[12:13], v242, s2, v[102:103]
	v_mad_i32_i24 v211, v243, s2, v211
	v_lshl_add_u64 v[210:211], v[210:211], 0, v[104:105]
	v_lshl_add_u64 v[216:217], s[20:21], 0, v[244:245]
	ds_read_b128 v[242:245], v218
	v_lshlrev_b64 v[250:251], 2, v[214:215]
	v_lshl_add_u64 v[214:215], v[210:211], 0, v[128:129]
	v_lshl_add_u64 v[210:211], s[52:53], 0, v[250:251]
	v_mad_u64_u32 v[102:103], s[12:13], v246, s2, v[102:103]
	v_mad_i32_i24 v103, v247, s2, v103
	v_lshl_add_u64 v[102:103], v[102:103], 0, v[104:105]
	v_lshl_add_u64 v[102:103], v[102:103], 0, v[128:129]
	s_waitcnt vmcnt(0) lgkmcnt(1)
	v_pk_add_f32 v[220:221], v[238:239], v[220:221]
	v_pk_add_f32 v[222:223], v[240:241], v[222:223]
	global_store_dwordx4 v[216:217], v[220:223], off
	s_nop 1
	v_cvt_pk_bf16_f32 v220, v220, v221
	v_cvt_pk_bf16_f32 v221, v222, v223
	global_store_dwordx2 v[214:215], v[220:221], off
	global_load_dwordx4 v[238:241], v[210:211], off
	v_lshlrev_b64 v[220:221], 11, v[246:247]
	v_lshl_add_u64 v[164:165], v[220:221], 0, v[164:165]
	v_lshlrev_b64 v[248:249], 2, v[164:165]
	v_lshl_add_u64 v[222:223], s[20:21], 0, v[250:251]
	v_lshl_add_u64 v[220:221], v[162:163], 0, v[128:129]
	v_lshl_add_u64 v[164:165], s[52:53], 0, v[248:249]
	v_lshl_add_u64 v[104:105], s[20:21], 0, v[248:249]
	s_waitcnt vmcnt(0) lgkmcnt(0)
	v_pk_add_f32 v[238:239], v[242:243], v[238:239]
	v_pk_add_f32 v[240:241], v[244:245], v[240:241]
	v_cvt_pk_bf16_f32 v162, v238, v239
	v_cvt_pk_bf16_f32 v163, v240, v241
	global_store_dwordx4 v[222:223], v[238:241], off
	global_store_dwordx2 v[220:221], v[162:163], off
	global_load_dwordx4 v[238:241], v[164:165], off
	v_mad_u64_u32 v[162:163], s[12:13], v148, s14, v[166:167]
	ds_read_b128 v[242:245], v162
	v_readlane_b32 s12, v254, 28
	s_add_i32 s16, s16, s12
	s_ashr_i32 s12, s16, 31
	s_lshr_b32 s12, s12, 27
	s_add_i32 s12, s16, s12
	s_ashr_i32 s12, s12, 5
	s_lshl_b32 s12, s12, 3
	v_readlane_b32 s13, v254, 24
	s_or_b32 s17, s12, s13
	s_cmp_gt_i32 s17, 31
	s_waitcnt vmcnt(0) lgkmcnt(0)
; __device__ __forceinline__ int accrow(int reg, int lh) { return (reg & 3) + 8 * (reg >> 2) + 4 * lh; }
; template <int EPI, int PN>
; __device__ void gemm_phase(const Params& p, const u16* __restrict__ A, const u16* __restrict__ Bt, int nNt, char* smem) {
;     ...
;       for (int j = 0; j < 2; ++j) {
; #pragma unroll
;         for (int i = 0; i < 4; ++i)
; #pragma unroll
;           for (int r = 0; r < 16; ++r) *(float*)(et + (i * 32 + accrow(r, lhE)) * 144 + lrE * 4) = acc[i][j][r];
; #pragma unroll
;         for (int it = 0; it < 16; ++it) {
;           const int c = it * 64 + laneE, row = c >> 3, seg = c & 7;
;           const float4 v = *(const float4*)(et + row * 144 + seg * 16);
;           const size_t g = (row0 + row) * DM + col0 + j * 32 + seg * 4;
;           const float4 xv = *(const float4*)(p.x + g);
;           const float4 hv = make_float4(xv.x + v.x, xv.y + v.y, xv.z + v.z, xv.w + v.w);
;           *(float4*)(p.out + g) = hv;
;           uint2 hb; hb.x = pack2(hv.x, hv.y); hb.y = pack2(hv.z, hv.w);
;           *(uint2*)(p.xn + (row0 + row) * LDK + col0 + j * 32 + seg * 4) = hb;
;         }
	v_pk_add_f32 v[238:239], v[242:243], v[238:239]
	v_pk_add_f32 v[240:241], v[244:245], v[240:241]
	v_cvt_pk_bf16_f32 v148, v238, v239
	v_cvt_pk_bf16_f32 v149, v240, v241
	global_store_dwordx4 v[104:105], v[238:241], off
	global_store_dwordx2 v[102:103], v[148:149], off
	global_load_dwordx4 v[238:241], v[160:161], off offset:128
	ds_write_b32 v159, v48
	ds_write_b32 v159, v49 offset:144
	ds_write_b32 v159, v50 offset:288
	ds_write_b32 v159, v51 offset:432
	ds_write_b32 v159, v52 offset:1152
	ds_write_b32 v159, v53 offset:1296
	ds_write_b32 v159, v54 offset:1440
	ds_write_b32 v159, v55 offset:1584
	ds_write_b32 v159, v56 offset:2304
	ds_write_b32 v159, v57 offset:2448
	ds_write_b32 v159, v58 offset:2592
	ds_write_b32 v159, v59 offset:2736
	ds_write_b32 v159, v60 offset:3456
	ds_write_b32 v159, v61 offset:3600
	ds_write_b32 v159, v62 offset:3744
	ds_write_b32 v159, v63 offset:3888
	ds_write_b32 v159, v32 offset:4608
	ds_write_b32 v159, v33 offset:4752
	ds_write_b32 v159, v34 offset:4896
	ds_write_b32 v159, v35 offset:5040
	ds_write_b32 v159, v36 offset:5760
	ds_write_b32 v159, v37 offset:5904
	ds_write_b32 v159, v38 offset:6048
	ds_write_b32 v159, v39 offset:6192
	ds_write_b32 v159, v40 offset:6912
	ds_write_b32 v159, v41 offset:7056
	ds_write_b32 v159, v42 offset:7200
	ds_write_b32 v159, v43 offset:7344
	ds_write_b32 v159, v44 offset:8064
	ds_write_b32 v159, v45 offset:8208
	ds_write_b32 v159, v46 offset:8352
	ds_write_b32 v159, v47 offset:8496
	ds_write_b32 v159, v16 offset:9216
	ds_write_b32 v159, v17 offset:9360
	ds_write_b32 v159, v18 offset:9504
	ds_write_b32 v159, v19 offset:9648
	ds_write_b32 v159, v20 offset:10368
	ds_write_b32 v159, v21 offset:10512
	ds_write_b32 v159, v22 offset:10656
	ds_write_b32 v159, v23 offset:10800
	ds_write_b32 v159, v24 offset:11520
	ds_write_b32 v159, v25 offset:11664
	ds_write_b32 v159, v26 offset:11808
	ds_write_b32 v159, v27 offset:11952
	ds_write_b32 v159, v28 offset:12672
	ds_write_b32 v159, v29 offset:12816
	ds_write_b32 v159, v30 offset:12960
	ds_write_b32 v159, v31 offset:13104
	ds_write_b32 v159, v0 offset:13824
	ds_write_b32 v159, v1 offset:13968
	ds_write_b32 v159, v2 offset:14112
	ds_write_b32 v159, v3 offset:14256
	ds_write_b32 v159, v4 offset:14976
	ds_write_b32 v159, v5 offset:15120
	ds_write_b32 v159, v6 offset:15264
	ds_write_b32 v159, v7 offset:15408
	ds_write_b32 v159, v8 offset:16128
	ds_write_b32 v159, v9 offset:16272
	ds_write_b32 v159, v10 offset:16416
	ds_write_b32 v159, v11 offset:16560
	ds_write_b32 v159, v12 offset:17280
	ds_write_b32 v159, v13 offset:17424
	ds_write_b32 v159, v14 offset:17568
	ds_write_b32 v159, v15 offset:17712
	ds_read_b128 v[0:3], v158
	ds_read_b128 v[4:7], v72
	s_waitcnt vmcnt(0) lgkmcnt(1)
	v_pk_add_f32 v[0:1], v[0:1], v[238:239]
	v_pk_add_f32 v[2:3], v[2:3], v[240:241]
	global_store_dwordx4 v[64:65], v[0:3], off offset:128
	s_nop 1
	v_cvt_pk_bf16_f32 v0, v0, v1
	v_cvt_pk_bf16_f32 v1, v2, v3
	global_store_dwordx2 v[66:67], v[0:1], off offset:64
	global_load_dwordx4 v[0:3], v[68:69], off offset:128
	s_waitcnt vmcnt(0) lgkmcnt(0)
	v_pk_add_f32 v[0:1], v[4:5], v[0:1]
	v_pk_add_f32 v[2:3], v[6:7], v[2:3]
	global_store_dwordx4 v[76:77], v[0:3], off offset:128
	ds_read_b128 v[4:7], v80
	s_nop 0
	v_cvt_pk_bf16_f32 v0, v0, v1
	v_cvt_pk_bf16_f32 v1, v2, v3
	global_store_dwordx2 v[74:75], v[0:1], off offset:64
	global_load_dwordx4 v[0:3], v[70:71], off offset:128
	s_waitcnt vmcnt(0) lgkmcnt(0)
	v_pk_add_f32 v[0:1], v[4:5], v[0:1]
	v_pk_add_f32 v[2:3], v[6:7], v[2:3]
	global_store_dwordx4 v[84:85], v[0:3], off offset:128
	ds_read_b128 v[4:7], v88
	s_nop 0
	v_cvt_pk_bf16_f32 v0, v0, v1
	v_cvt_pk_bf16_f32 v1, v2, v3
	global_store_dwordx2 v[82:83], v[0:1], off offset:64
	global_load_dwordx4 v[0:3], v[78:79], off offset:128
	s_waitcnt vmcnt(0) lgkmcnt(0)
	v_pk_add_f32 v[0:1], v[4:5], v[0:1]
	v_pk_add_f32 v[2:3], v[6:7], v[2:3]
	global_store_dwordx4 v[92:93], v[0:3], off offset:128
	ds_read_b128 v[4:7], v96
	s_nop 0
	v_cvt_pk_bf16_f32 v0, v0, v1
	v_cvt_pk_bf16_f32 v1, v2, v3
	global_store_dwordx2 v[90:91], v[0:1], off offset:64
	global_load_dwordx4 v[0:3], v[86:87], off offset:128
	s_waitcnt vmcnt(0) lgkmcnt(0)
; template <int EPI, int PN>
; __device__ void gemm_phase(const Params& p, const u16* __restrict__ A, const u16* __restrict__ Bt, int nNt, char* smem) {
;     ...
;         for (int it = 0; it < 16; ++it) {
;           const int c = it * 64 + laneE, row = c >> 3, seg = c & 7;
;           const float4 v = *(const float4*)(et + row * 144 + seg * 16);
;           const size_t g = (row0 + row) * DM + col0 + j * 32 + seg * 4;
;           const float4 xv = *(const float4*)(p.x + g);
;           const float4 hv = make_float4(xv.x + v.x, xv.y + v.y, xv.z + v.z, xv.w + v.w);
;           *(float4*)(p.out + g) = hv;
;           uint2 hb; hb.x = pack2(hv.x, hv.y); hb.y = pack2(hv.z, hv.w);
;           *(uint2*)(p.xn + (row0 + row) * LDK + col0 + j * 32 + seg * 4) = hb;
;         }
;     ...
;     __syncthreads();
;   }
	v_pk_add_f32 v[0:1], v[4:5], v[0:1]
	v_pk_add_f32 v[2:3], v[6:7], v[2:3]
	global_store_dwordx4 v[100:101], v[0:3], off offset:128
	ds_read_b128 v[4:7], v108
	s_nop 0
	v_cvt_pk_bf16_f32 v0, v0, v1
	v_cvt_pk_bf16_f32 v1, v2, v3
	global_store_dwordx2 v[98:99], v[0:1], off offset:64
	global_load_dwordx4 v[0:3], v[94:95], off offset:128
	s_waitcnt vmcnt(0) lgkmcnt(0)
	v_pk_add_f32 v[0:1], v[4:5], v[0:1]
	v_pk_add_f32 v[2:3], v[6:7], v[2:3]
	global_store_dwordx4 v[112:113], v[0:3], off offset:128
	ds_read_b128 v[4:7], v116
	s_nop 0
	v_cvt_pk_bf16_f32 v0, v0, v1
	v_cvt_pk_bf16_f32 v1, v2, v3
	global_store_dwordx2 v[110:111], v[0:1], off offset:64
	global_load_dwordx4 v[0:3], v[106:107], off offset:128
	s_waitcnt vmcnt(0) lgkmcnt(0)
	v_pk_add_f32 v[0:1], v[4:5], v[0:1]
	v_pk_add_f32 v[2:3], v[6:7], v[2:3]
	global_store_dwordx4 v[120:121], v[0:3], off offset:128
	ds_read_b128 v[4:7], v124
	s_nop 0
	v_cvt_pk_bf16_f32 v0, v0, v1
	v_cvt_pk_bf16_f32 v1, v2, v3
	global_store_dwordx2 v[118:119], v[0:1], off offset:64
	global_load_dwordx4 v[0:3], v[114:115], off offset:128
	s_waitcnt vmcnt(0) lgkmcnt(0)
	v_pk_add_f32 v[0:1], v[4:5], v[0:1]
	v_pk_add_f32 v[2:3], v[6:7], v[2:3]
	global_store_dwordx4 v[168:169], v[0:3], off offset:128
	ds_read_b128 v[4:7], v172
	s_nop 0
	v_cvt_pk_bf16_f32 v0, v0, v1
	v_cvt_pk_bf16_f32 v1, v2, v3
	global_store_dwordx2 v[126:127], v[0:1], off offset:64
	global_load_dwordx4 v[0:3], v[122:123], off offset:128
	s_waitcnt vmcnt(0) lgkmcnt(0)
	v_pk_add_f32 v[0:1], v[4:5], v[0:1]
	v_pk_add_f32 v[2:3], v[6:7], v[2:3]
	global_store_dwordx4 v[176:177], v[0:3], off offset:128
	ds_read_b128 v[4:7], v180
	s_nop 0
	v_cvt_pk_bf16_f32 v0, v0, v1
	v_cvt_pk_bf16_f32 v1, v2, v3
	global_store_dwordx2 v[174:175], v[0:1], off offset:64
	global_load_dwordx4 v[0:3], v[170:171], off offset:128
	s_waitcnt vmcnt(0) lgkmcnt(0)
	v_pk_add_f32 v[0:1], v[4:5], v[0:1]
	v_pk_add_f32 v[2:3], v[6:7], v[2:3]
	global_store_dwordx4 v[184:185], v[0:3], off offset:128
	ds_read_b128 v[4:7], v188
	s_nop 0
	v_cvt_pk_bf16_f32 v0, v0, v1
	v_cvt_pk_bf16_f32 v1, v2, v3
	global_store_dwordx2 v[182:183], v[0:1], off offset:64
	global_load_dwordx4 v[0:3], v[178:179], off offset:128
	s_waitcnt vmcnt(0) lgkmcnt(0)
	v_pk_add_f32 v[0:1], v[4:5], v[0:1]
	v_pk_add_f32 v[2:3], v[6:7], v[2:3]
	global_store_dwordx4 v[192:193], v[0:3], off offset:128
	ds_read_b128 v[4:7], v196
	s_nop 0
	v_cvt_pk_bf16_f32 v0, v0, v1
	v_cvt_pk_bf16_f32 v1, v2, v3
	global_store_dwordx2 v[190:191], v[0:1], off offset:64
	global_load_dwordx4 v[0:3], v[186:187], off offset:128
	s_waitcnt vmcnt(0) lgkmcnt(0)
	v_pk_add_f32 v[0:1], v[4:5], v[0:1]
	v_pk_add_f32 v[2:3], v[6:7], v[2:3]
	global_store_dwordx4 v[200:201], v[0:3], off offset:128
	ds_read_b128 v[4:7], v204
	s_nop 0
	v_cvt_pk_bf16_f32 v0, v0, v1
	v_cvt_pk_bf16_f32 v1, v2, v3
	global_store_dwordx2 v[198:199], v[0:1], off offset:64
	global_load_dwordx4 v[0:3], v[194:195], off offset:128
	s_waitcnt vmcnt(0) lgkmcnt(0)
	v_pk_add_f32 v[0:1], v[4:5], v[0:1]
	v_pk_add_f32 v[2:3], v[6:7], v[2:3]
	global_store_dwordx4 v[208:209], v[0:3], off offset:128
	ds_read_b128 v[4:7], v212
	s_nop 0
	v_cvt_pk_bf16_f32 v0, v0, v1
	v_cvt_pk_bf16_f32 v1, v2, v3
	global_store_dwordx2 v[206:207], v[0:1], off offset:64
	global_load_dwordx4 v[0:3], v[202:203], off offset:128
	s_waitcnt vmcnt(0) lgkmcnt(0)
	v_pk_add_f32 v[0:1], v[4:5], v[0:1]
	v_pk_add_f32 v[2:3], v[6:7], v[2:3]
	global_store_dwordx4 v[216:217], v[0:3], off offset:128
	ds_read_b128 v[4:7], v218
	s_nop 0
	v_cvt_pk_bf16_f32 v0, v0, v1
	v_cvt_pk_bf16_f32 v1, v2, v3
	global_store_dwordx2 v[214:215], v[0:1], off offset:64
	global_load_dwordx4 v[0:3], v[210:211], off offset:128
	s_waitcnt vmcnt(0) lgkmcnt(0)
	v_pk_add_f32 v[0:1], v[4:5], v[0:1]
	v_pk_add_f32 v[2:3], v[6:7], v[2:3]
	global_store_dwordx4 v[222:223], v[0:3], off offset:128
	ds_read_b128 v[4:7], v162
	s_nop 0
	v_cvt_pk_bf16_f32 v0, v0, v1
	v_cvt_pk_bf16_f32 v1, v2, v3
	global_store_dwordx2 v[220:221], v[0:1], off offset:64
	global_load_dwordx4 v[0:3], v[164:165], off offset:128
	s_waitcnt vmcnt(0) lgkmcnt(0)
	v_pk_add_f32 v[0:1], v[4:5], v[0:1]
	v_pk_add_f32 v[2:3], v[6:7], v[2:3]
	global_store_dwordx4 v[104:105], v[0:3], off offset:128
	s_nop 1
	v_cvt_pk_bf16_f32 v0, v0, v1
	v_cvt_pk_bf16_f32 v1, v2, v3
	global_store_dwordx2 v[102:103], v[0:1], off offset:64
	s_barrier
	s_cbranch_scc0 .LBB0_665

; template <int EPI, int PN>
; __device__ void gemm_phase(const Params& p, const u16* __restrict__ A, const u16* __restrict__ Bt, int nNt, char* smem) {
;     ...
;     for (int kt = 0; kt < 32; ++kt) {
;       asm volatile("s_waitcnt vmcnt(0)" ::: "memory");
;       __builtin_amdgcn_s_barrier();
;       const u16* Ab = ring + (kt & 1) * STG;
;       const u16* Bb = Ab + 16384;
;       u16* st = ring + ((kt + 1) & 1) * STG;
;       const bool pre = (kt + 1 < 32);
;       s16x8 af[2][4], bf[2][2];
;       auto ldfrag = [&](int ks, int slot) {
; #pragma unroll
;         for (int i = 0; i < 4; ++i) {
;           const int row = wr * 128 + i * 32 + lr;
;           af[slot][i] = *(const s16x8*)(Ab + row * 64 + (((ks * 2 + lh) ^ ((row >> 1) & 7)) * 8));
;         }
; #pragma unroll
;         for (int j = 0; j < 2; ++j) {
;           const int rowb = nh * 128 + wc * 64 + j * 32 + lr;
;           bf[slot][j] = *(const s16x8*)(Bb + rowb * 64 + (((ks * 2 + lh) ^ ((rowb >> 1) & 7)) * 8));
;         }
;       };
;       ldfrag(0, 0);
;       ldfrag(1, 1);
;       __builtin_amdgcn_sched_barrier(0);
; #pragma unroll
;       for (int ks = 0; ks < 4; ++ks) {
;         const int slot = ks & 1;
; #pragma unroll
;         for (int i = 0; i < 4; ++i) {
;           acc[i][0] = mfma32(af[slot][i], bf[slot][0], acc[i][0]);
;           acc[i][1] = mfma32(af[slot][i], bf[slot][1], acc[i][1]);
;           __builtin_amdgcn_sched_barrier(0);
;           if (pre && (i & 1) == 0) {
;             const int pi = ks * 2 + (i >> 1);
;             if (pi < 4) glds16(Ag0 + (size_t)pi * 64 * LDK + (kt + 1) * 64, st + (srow + 64 * pi) * 64 + sch * 8);
;             else glds16(Bg0 + (size_t)(pi - 4) * 64 * LDK + (kt + 1) * 64, st + 16384 + (srow + 64 * (pi - 4)) * 64 + sch * 8);
;             __builtin_amdgcn_sched_barrier(0);
;           }
;         }
;         if (ks + 2 < 4) { ldfrag(ks + 2, slot); __builtin_amdgcn_sched_barrier(0); }
;       }
.Lrot723_loop:
	s_add_i32 s15, s11, 0xffff8000
	s_and_b32 s15, s15, 0x8000
	s_lshl_b32 s15, s15, 1
	v_lshl_or_b32 v128, v143, 1, s15
	v_lshl_add_u32 v149, v147, 1, s15
	s_and_b32 s98, s11, 0x8000
	s_lshl_b32 s98, s98, 1
	s_waitcnt lgkmcnt(7)
	v_mfma_f32_32x32x16_bf16 v[112:127], v[178:181], v[194:197], v[112:127]
	v_add3_u32 v226, s98, v162, v156
	s_waitcnt lgkmcnt(6)
	v_mfma_f32_32x32x16_bf16 v[96:111], v[178:181], v[198:201], v[96:111]
	v_readfirstlane_b32 s100, v226
	s_mov_b32 s16, m0
	s_add_i32 m0, s100, 0x8000
	s_nop 0
	global_load_lds_dwordx4 v[160:161], off
	v_mfma_f32_32x32x16_bf16 v[80:95], v[182:185], v[194:197], v[80:95]
	v_lshl_add_u64 v[178:179], v[160:161], 0, s[2:3]
	s_add_i32 m0, s100, 0xa000
	s_nop 0
	global_load_lds_dwordx4 v[178:179], off
	v_mfma_f32_32x32x16_bf16 v[64:79], v[182:185], v[198:201], v[64:79]
	v_lshl_add_u64 v[180:181], v[160:161], 0, s[4:5]
	s_add_i32 m0, s100, 0xc000
	s_nop 0
	global_load_lds_dwordx4 v[180:181], off
	v_mfma_f32_32x32x16_bf16 v[48:63], v[186:189], v[194:197], v[48:63]
	v_lshl_add_u64 v[178:179], v[160:161], 0, s[6:7]
	s_add_i32 m0, s100, 0xe000
	s_nop 0
	global_load_lds_dwordx4 v[178:179], off
	s_mov_b32 m0, s16
	v_mfma_f32_32x32x16_bf16 v[32:47], v[186:189], v[198:201], v[32:47]
	v_mfma_f32_32x32x16_bf16 v[16:31], v[190:193], v[194:197], v[16:31]
	v_mfma_f32_32x32x16_bf16 v[0:15], v[190:193], v[198:201], v[0:15]
	v_lshl_add_u64 v[160:161], v[160:161], 0, s[8:9]
	v_add_u32_e32 v177, v128, v175
	ds_read_b128 v[178:181], v177
	ds_read_b128 v[182:185], v177 offset:4096
	ds_read_b128 v[186:189], v177 offset:8192
	ds_read_b128 v[190:193], v177 offset:12288
	v_add_u32_e32 v177, v149, v175
	ds_read_b128 v[194:197], v177 offset:32768
	ds_read_b128 v[198:201], v177 offset:36864
	s_waitcnt lgkmcnt(7)
	v_mfma_f32_32x32x16_bf16 v[112:127], v[202:205], v[218:221], v[112:127]
	s_waitcnt lgkmcnt(6)
	v_mfma_f32_32x32x16_bf16 v[96:111], v[202:205], v[222:225], v[96:111]
	v_mfma_f32_32x32x16_bf16 v[80:95], v[206:209], v[218:221], v[80:95]
	v_mfma_f32_32x32x16_bf16 v[64:79], v[206:209], v[222:225], v[64:79]
	v_mfma_f32_32x32x16_bf16 v[48:63], v[210:213], v[218:221], v[48:63]
	v_mfma_f32_32x32x16_bf16 v[32:47], v[210:213], v[222:225], v[32:47]
	v_mfma_f32_32x32x16_bf16 v[16:31], v[214:217], v[218:221], v[16:31]
	v_mfma_f32_32x32x16_bf16 v[0:15], v[214:217], v[222:225], v[0:15]
	v_add_u32_e32 v128, v128, v176
	ds_read_b128 v[202:205], v128
	ds_read_b128 v[206:209], v128 offset:4096
	ds_read_b128 v[210:213], v128 offset:8192
	ds_read_b128 v[214:217], v128 offset:12288
	v_add_u32_e32 v128, v149, v176
	ds_read_b128 v[218:221], v128 offset:32768
	ds_read_b128 v[222:225], v128 offset:36864
	s_waitcnt lgkmcnt(7)
	v_mfma_f32_32x32x16_bf16 v[112:127], v[178:181], v[194:197], v[112:127]
	s_waitcnt lgkmcnt(6)
	v_mfma_f32_32x32x16_bf16 v[96:111], v[178:181], v[198:201], v[96:111]
	v_mfma_f32_32x32x16_bf16 v[80:95], v[182:185], v[194:197], v[80:95]
	v_mfma_f32_32x32x16_bf16 v[64:79], v[182:185], v[198:201], v[64:79]
	v_mfma_f32_32x32x16_bf16 v[48:63], v[186:189], v[194:197], v[48:63]
	v_mfma_f32_32x32x16_bf16 v[32:47], v[186:189], v[198:201], v[32:47]
	v_mfma_f32_32x32x16_bf16 v[16:31], v[190:193], v[194:197], v[16:31]
	v_mfma_f32_32x32x16_bf16 v[0:15], v[190:193], v[198:201], v[0:15]
	s_waitcnt vmcnt(0) lgkmcnt(0)
	s_barrier
	v_lshl_or_b32 v227, v143, 1, s98
	v_lshl_add_u32 v229, v147, 1, s98
	v_add_u32_e32 v228, v227, v173
	v_add_u32_e32 v230, v229, v173
	ds_read_b128 v[178:181], v228
	ds_read_b128 v[182:185], v228 offset:4096
	ds_read_b128 v[186:189], v228 offset:8192
	ds_read_b128 v[190:193], v228 offset:12288
	ds_read_b128 v[194:197], v230 offset:32768
	ds_read_b128 v[198:201], v230 offset:36864
	v_add3_u32 v226, s15, v162, v156
	v_mfma_f32_32x32x16_bf16 v[112:127], v[202:205], v[218:221], v[112:127]
	v_readfirstlane_b32 s99, v226
	s_mov_b32 s16, m0
	s_mov_b32 m0, s99
	s_nop 0
	global_load_lds_dwordx4 v[158:159], off
	v_mfma_f32_32x32x16_bf16 v[96:111], v[202:205], v[222:225], v[96:111]
	v_lshl_add_u64 v[232:233], v[158:159], 0, s[2:3]
	s_add_i32 m0, s99, 0x2000
	s_nop 0
	global_load_lds_dwordx4 v[232:233], off
	v_mfma_f32_32x32x16_bf16 v[80:95], v[206:209], v[218:221], v[80:95]
	v_lshl_add_u64 v[234:235], v[158:159], 0, s[4:5]
	s_add_i32 m0, s99, 0x4000
	s_nop 0
	global_load_lds_dwordx4 v[234:235], off
	v_mfma_f32_32x32x16_bf16 v[64:79], v[206:209], v[222:225], v[64:79]
	v_lshl_add_u64 v[232:233], v[158:159], 0, s[6:7]
	s_add_i32 m0, s99, 0x6000
	s_nop 0
	global_load_lds_dwordx4 v[232:233], off
	s_mov_b32 m0, s16
	v_mfma_f32_32x32x16_bf16 v[48:63], v[210:213], v[218:221], v[48:63]
	v_mfma_f32_32x32x16_bf16 v[32:47], v[210:213], v[222:225], v[32:47]
	v_mfma_f32_32x32x16_bf16 v[16:31], v[214:217], v[218:221], v[16:31]
	v_mfma_f32_32x32x16_bf16 v[0:15], v[214:217], v[222:225], v[0:15]
	v_add_u32_e32 v228, v227, v174
	v_add_u32_e32 v230, v229, v174
	ds_read_b128 v[202:205], v228
	ds_read_b128 v[206:209], v228 offset:4096
	ds_read_b128 v[210:213], v228 offset:8192
	ds_read_b128 v[214:217], v228 offset:12288
	ds_read_b128 v[218:221], v230 offset:32768
	ds_read_b128 v[222:225], v230 offset:36864
	s_add_i32 s11, s11, 0x8000
	v_lshl_add_u64 v[158:159], v[158:159], 0, s[8:9]
	s_cmp_eq_u32 s11, 0xf8000
	s_cbranch_scc0 .Lrot723_loop
; template <int EPI, int PN>
; __device__ void gemm_phase(const Params& p, const u16* __restrict__ A, const u16* __restrict__ Bt, int nNt, char* smem) {
;     ...
;     for (int kt = 0; kt < 32; ++kt) {
;       asm volatile("s_waitcnt vmcnt(0)" ::: "memory");
;       __builtin_amdgcn_s_barrier();
;       const u16* Ab = ring + (kt & 1) * STG;
;       const u16* Bb = Ab + 16384;
;       u16* st = ring + ((kt + 1) & 1) * STG;
;       const bool pre = (kt + 1 < 32);
;       s16x8 af[2][4], bf[2][2];
;       auto ldfrag = [&](int ks, int slot) {
; #pragma unroll
;         for (int i = 0; i < 4; ++i) {
;           const int row = wr * 128 + i * 32 + lr;
;           af[slot][i] = *(const s16x8*)(Ab + row * 64 + (((ks * 2 + lh) ^ ((row >> 1) & 7)) * 8));
;         }
; #pragma unroll
;         for (int j = 0; j < 2; ++j) {
;           const int rowb = nh * 128 + wc * 64 + j * 32 + lr;
;           bf[slot][j] = *(const s16x8*)(Bb + rowb * 64 + (((ks * 2 + lh) ^ ((rowb >> 1) & 7)) * 8));
;         }
;       };
;       ldfrag(0, 0);
;       ldfrag(1, 1);
;       __builtin_amdgcn_sched_barrier(0);
; #pragma unroll
;       for (int ks = 0; ks < 4; ++ks) {
;         const int slot = ks & 1;
; #pragma unroll
;         for (int i = 0; i < 4; ++i) {
;           acc[i][0] = mfma32(af[slot][i], bf[slot][0], acc[i][0]);
;           acc[i][1] = mfma32(af[slot][i], bf[slot][1], acc[i][1]);
;           __builtin_amdgcn_sched_barrier(0);
;           if (pre && (i & 1) == 0) {
;             const int pi = ks * 2 + (i >> 1);
;             if (pi < 4) glds16(Ag0 + (size_t)pi * 64 * LDK + (kt + 1) * 64, st + (srow + 64 * pi) * 64 + sch * 8);
;             else glds16(Bg0 + (size_t)(pi - 4) * 64 * LDK + (kt + 1) * 64, st + 16384 + (srow + 64 * (pi - 4)) * 64 + sch * 8);
;             __builtin_amdgcn_sched_barrier(0);
;           }
;         }
;         if (ks + 2 < 4) { ldfrag(ks + 2, slot); __builtin_amdgcn_sched_barrier(0); }
;       }
	s_add_i32 s15, s11, 0xffff8000
	s_and_b32 s15, s15, 0x8000
	s_lshl_b32 s15, s15, 1
	v_lshl_or_b32 v128, v143, 1, s15
	v_lshl_add_u32 v149, v147, 1, s15
	s_and_b32 s98, s11, 0x8000
	s_lshl_b32 s98, s98, 1
	s_waitcnt lgkmcnt(7)
	v_mfma_f32_32x32x16_bf16 v[112:127], v[178:181], v[194:197], v[112:127]
	v_add3_u32 v226, s98, v162, v156
	s_waitcnt lgkmcnt(6)
	v_mfma_f32_32x32x16_bf16 v[96:111], v[178:181], v[198:201], v[96:111]
	v_readfirstlane_b32 s100, v226
	s_mov_b32 s16, m0
	s_add_i32 m0, s100, 0x8000
	s_nop 0
	global_load_lds_dwordx4 v[160:161], off
	v_mfma_f32_32x32x16_bf16 v[80:95], v[182:185], v[194:197], v[80:95]
	v_lshl_add_u64 v[178:179], v[160:161], 0, s[2:3]
	s_add_i32 m0, s100, 0xa000
	s_nop 0
	global_load_lds_dwordx4 v[178:179], off
	v_mfma_f32_32x32x16_bf16 v[64:79], v[182:185], v[198:201], v[64:79]
	v_lshl_add_u64 v[180:181], v[160:161], 0, s[4:5]
	s_add_i32 m0, s100, 0xc000
	s_nop 0
	global_load_lds_dwordx4 v[180:181], off
	v_mfma_f32_32x32x16_bf16 v[48:63], v[186:189], v[194:197], v[48:63]
	v_lshl_add_u64 v[178:179], v[160:161], 0, s[6:7]
	s_add_i32 m0, s100, 0xe000
	s_nop 0
	global_load_lds_dwordx4 v[178:179], off
	s_mov_b32 m0, s16
	v_mfma_f32_32x32x16_bf16 v[32:47], v[186:189], v[198:201], v[32:47]
	v_mfma_f32_32x32x16_bf16 v[16:31], v[190:193], v[194:197], v[16:31]
	v_mfma_f32_32x32x16_bf16 v[0:15], v[190:193], v[198:201], v[0:15]
	v_lshl_add_u64 v[160:161], v[160:161], 0, s[8:9]
	v_add_u32_e32 v177, v128, v175
	ds_read_b128 v[178:181], v177
	ds_read_b128 v[182:185], v177 offset:4096
	ds_read_b128 v[186:189], v177 offset:8192
	ds_read_b128 v[190:193], v177 offset:12288
	v_add_u32_e32 v177, v149, v175
	ds_read_b128 v[194:197], v177 offset:32768
	ds_read_b128 v[198:201], v177 offset:36864
	s_waitcnt lgkmcnt(7)
	v_mfma_f32_32x32x16_bf16 v[112:127], v[202:205], v[218:221], v[112:127]
	s_waitcnt lgkmcnt(6)
	v_mfma_f32_32x32x16_bf16 v[96:111], v[202:205], v[222:225], v[96:111]
	v_mfma_f32_32x32x16_bf16 v[80:95], v[206:209], v[218:221], v[80:95]
	v_mfma_f32_32x32x16_bf16 v[64:79], v[206:209], v[222:225], v[64:79]
	v_mfma_f32_32x32x16_bf16 v[48:63], v[210:213], v[218:221], v[48:63]
	v_mfma_f32_32x32x16_bf16 v[32:47], v[210:213], v[222:225], v[32:47]
	v_mfma_f32_32x32x16_bf16 v[16:31], v[214:217], v[218:221], v[16:31]
	v_mfma_f32_32x32x16_bf16 v[0:15], v[214:217], v[222:225], v[0:15]
	v_add_u32_e32 v128, v128, v176
	ds_read_b128 v[202:205], v128
	ds_read_b128 v[206:209], v128 offset:4096
	ds_read_b128 v[210:213], v128 offset:8192
	ds_read_b128 v[214:217], v128 offset:12288
	v_add_u32_e32 v128, v149, v176
	ds_read_b128 v[218:221], v128 offset:32768
	ds_read_b128 v[222:225], v128 offset:36864
	s_waitcnt lgkmcnt(7)
	v_mfma_f32_32x32x16_bf16 v[112:127], v[178:181], v[194:197], v[112:127]
	s_waitcnt lgkmcnt(6)
	v_mfma_f32_32x32x16_bf16 v[96:111], v[178:181], v[198:201], v[96:111]
	v_mfma_f32_32x32x16_bf16 v[80:95], v[182:185], v[194:197], v[80:95]
	v_mfma_f32_32x32x16_bf16 v[64:79], v[182:185], v[198:201], v[64:79]
	v_mfma_f32_32x32x16_bf16 v[48:63], v[186:189], v[194:197], v[48:63]
	v_mfma_f32_32x32x16_bf16 v[32:47], v[186:189], v[198:201], v[32:47]
	v_mfma_f32_32x32x16_bf16 v[16:31], v[190:193], v[194:197], v[16:31]
	v_mfma_f32_32x32x16_bf16 v[0:15], v[190:193], v[198:201], v[0:15]
	s_waitcnt lgkmcnt(1)
	v_mfma_f32_32x32x16_bf16 v[112:127], v[202:205], v[218:221], v[112:127]
	s_waitcnt lgkmcnt(0)
	v_mfma_f32_32x32x16_bf16 v[96:111], v[202:205], v[222:225], v[96:111]
	v_mfma_f32_32x32x16_bf16 v[80:95], v[206:209], v[218:221], v[80:95]
	v_mfma_f32_32x32x16_bf16 v[64:79], v[206:209], v[222:225], v[64:79]
	v_mfma_f32_32x32x16_bf16 v[48:63], v[210:213], v[218:221], v[48:63]
	v_mfma_f32_32x32x16_bf16 v[32:47], v[210:213], v[222:225], v[32:47]
	v_mfma_f32_32x32x16_bf16 v[16:31], v[214:217], v[218:221], v[16:31]
	v_mfma_f32_32x32x16_bf16 v[0:15], v[214:217], v[222:225], v[0:15]
	s_waitcnt vmcnt(0)
	s_barrier
	ds_read_b128 v[158:161], v164
	ds_read_b128 v[178:181], v164 offset:4096
	ds_read_b128 v[182:185], v164 offset:8192
	ds_read_b128 v[186:189], v164 offset:12288
	ds_read_b128 v[190:193], v165
	ds_read_b128 v[194:197], v165 offset:4096
	ds_read_b128 v[198:201], v166
	ds_read_b128 v[202:205], v166 offset:4096
	ds_read_b128 v[206:209], v166 offset:8192
	ds_read_b128 v[210:213], v166 offset:12288
	ds_read_b128 v[214:217], v168
	ds_read_b128 v[218:221], v168 offset:4096
	s_waitcnt lgkmcnt(7)
	v_mfma_f32_32x32x16_bf16 v[112:127], v[158:161], v[190:193], v[112:127]
	s_waitcnt lgkmcnt(6)
	v_mfma_f32_32x32x16_bf16 v[96:111], v[158:161], v[194:197], v[96:111]
	v_mfma_f32_32x32x16_bf16 v[80:95], v[178:181], v[190:193], v[80:95]
	v_mfma_f32_32x32x16_bf16 v[64:79], v[178:181], v[194:197], v[64:79]
	v_mfma_f32_32x32x16_bf16 v[48:63], v[182:185], v[190:193], v[48:63]
	v_mfma_f32_32x32x16_bf16 v[32:47], v[182:185], v[194:197], v[32:47]
	v_mfma_f32_32x32x16_bf16 v[16:31], v[186:189], v[190:193], v[16:31]
	v_mfma_f32_32x32x16_bf16 v[0:15], v[186:189], v[194:197], v[0:15]
	ds_read_b128 v[158:161], v169
	ds_read_b128 v[178:181], v169 offset:4096
	ds_read_b128 v[182:185], v169 offset:8192
	ds_read_b128 v[186:189], v169 offset:12288
	ds_read_b128 v[190:193], v170
	ds_read_b128 v[194:197], v170 offset:4096
	s_waitcnt lgkmcnt(7)
	v_mfma_f32_32x32x16_bf16 v[112:127], v[198:201], v[214:217], v[112:127]
	s_waitcnt lgkmcnt(6)
; template <int EPI, int PN>
; __device__ void gemm_phase(const Params& p, const u16* __restrict__ A, const u16* __restrict__ Bt, int nNt, char* smem) {
;     ...
;       for (int ks = 0; ks < 4; ++ks) {
;         const int slot = ks & 1;
; #pragma unroll
;         for (int i = 0; i < 4; ++i) {
;           acc[i][0] = mfma32(af[slot][i], bf[slot][0], acc[i][0]);
;           acc[i][1] = mfma32(af[slot][i], bf[slot][1], acc[i][1]);
;     ...
;     __syncthreads();
;     int mte = __builtin_amdgcn_readfirstlane(mt), nte = __builtin_amdgcn_readfirstlane(nt), lrE = lr, lhE = lh, laneE = lane;
;     asm volatile("" : "+s"(mte), "+s"(nte), "+v"(lrE), "+v"(lhE), "+v"(laneE));
;     unsigned char* et = (unsigned char*)smem + wv * 18432;
;     const int col0 = nte * 256 + nh * 128 + wc * 64;
;     const size_t row0 = (size_t)mte * 256 + wr * 128;
;     if (EPI == 1) {
; #pragma unroll
;       for (int j = 0; j < 2; ++j) {
; #pragma unroll
;         for (int i = 0; i < 4; ++i)
; #pragma unroll
;           for (int r = 0; r < 16; ++r) *(float*)(et + (i * 32 + accrow(r, lhE)) * 144 + lrE * 4) = acc[i][j][r];
; #pragma unroll
;         for (int it = 0; it < 16; ++it) {
;           const int c = it * 64 + laneE, row = c >> 3, seg = c & 7;
;           const float4 v = *(const float4*)(et + row * 144 + seg * 16);
;           const size_t g = (row0 + row) * DM + col0 + j * 32 + seg * 4;
;           const float4 xv = *(const float4*)(p.x + g);
;           const float4 hv = make_float4(xv.x + v.x, xv.y + v.y, xv.z + v.z, xv.w + v.w);
;           *(float4*)(p.out + g) = hv;
;           uint2 hb; hb.x = pack2(hv.x, hv.y); hb.y = pack2(hv.z, hv.w);
;           *(uint2*)(p.xn + (row0 + row) * LDK + col0 + j * 32 + seg * 4) = hb;
;         }
;       }
;     } else if (EPI == 0 && col0 >= NPROJ) {
; #pragma unroll
;       for (int i = 0; i < 4; ++i)
; #pragma unroll
;         for (int r = 0; r < 16; ++r) {
;           const size_t row = row0 + i * 32 + accrow(r, lhE);
;           const int col = col0 + lrE;
;           if (col < NIN) p.dtraw[row * 16 + (col - NPROJ)] = acc[i][0][r];
;         }
;     } else {
; #pragma unroll
;       for (int i = 0; i < 4; ++i)
; #pragma unroll
;         for (int j = 0; j < 2; ++j)
; #pragma unroll
;           for (int r = 0; r < 16; ++r) *(u16*)(et + (i * 32 + accrow(r, lhE)) * 144 + (j * 32 + lrE) * 2) = f2bf(acc[i][j][r]);
	v_mfma_f32_32x32x16_bf16 v[96:111], v[198:201], v[218:221], v[96:111]
	v_mfma_f32_32x32x16_bf16 v[80:95], v[202:205], v[214:217], v[80:95]
	v_mfma_f32_32x32x16_bf16 v[64:79], v[202:205], v[218:221], v[64:79]
	v_mfma_f32_32x32x16_bf16 v[48:63], v[206:209], v[214:217], v[48:63]
	v_mfma_f32_32x32x16_bf16 v[32:47], v[206:209], v[218:221], v[32:47]
	v_mfma_f32_32x32x16_bf16 v[16:31], v[210:213], v[214:217], v[16:31]
	v_mfma_f32_32x32x16_bf16 v[0:15], v[210:213], v[218:221], v[0:15]
	ds_read_b128 v[198:201], v171
	ds_read_b128 v[202:205], v171 offset:4096
	ds_read_b128 v[206:209], v171 offset:8192
	ds_read_b128 v[210:213], v171 offset:12288
	ds_read_b128 v[214:217], v172
	ds_read_b128 v[218:221], v172 offset:4096
	s_waitcnt lgkmcnt(7)
	v_mfma_f32_32x32x16_bf16 v[112:127], v[158:161], v[190:193], v[112:127]
	s_waitcnt lgkmcnt(6)
	v_mfma_f32_32x32x16_bf16 v[96:111], v[158:161], v[194:197], v[96:111]
	v_mfma_f32_32x32x16_bf16 v[80:95], v[178:181], v[190:193], v[80:95]
	v_mfma_f32_32x32x16_bf16 v[64:79], v[178:181], v[194:197], v[64:79]
	v_mfma_f32_32x32x16_bf16 v[48:63], v[182:185], v[190:193], v[48:63]
	v_mfma_f32_32x32x16_bf16 v[32:47], v[182:185], v[194:197], v[32:47]
	v_mfma_f32_32x32x16_bf16 v[16:31], v[186:189], v[190:193], v[16:31]
	v_mfma_f32_32x32x16_bf16 v[0:15], v[186:189], v[194:197], v[0:15]
	s_waitcnt lgkmcnt(1)
	v_mfma_f32_32x32x16_bf16 v[112:127], v[198:201], v[214:217], v[112:127]
	s_waitcnt lgkmcnt(0)
	v_mfma_f32_32x32x16_bf16 v[96:111], v[198:201], v[218:221], v[96:111]
	v_mfma_f32_32x32x16_bf16 v[80:95], v[202:205], v[214:217], v[80:95]
	v_mfma_f32_32x32x16_bf16 v[64:79], v[202:205], v[218:221], v[64:79]
	v_mfma_f32_32x32x16_bf16 v[48:63], v[206:209], v[214:217], v[48:63]
	v_mfma_f32_32x32x16_bf16 v[32:47], v[206:209], v[218:221], v[32:47]
	v_mfma_f32_32x32x16_bf16 v[16:31], v[210:213], v[214:217], v[16:31]
	v_mfma_f32_32x32x16_bf16 v[0:15], v[210:213], v[218:221], v[0:15]
	v_mov_b32_e32 v149, v135
	v_mov_b32_e32 v128, v139
	v_mov_b32_e32 v158, v137
	s_barrier
	s_nop 7
	v_cvt_pk_bf16_f32 v0, v0, s0
	v_lshlrev_b32_e32 v158, 1, v158
	v_mul_lo_u32 v128, v128, s12
	v_add3_u32 v128, v163, v158, v128
	v_cvt_pk_bf16_f32 v112, v112, s0
	v_cvt_pk_bf16_f32 v96, v96, s0
	v_cvt_pk_bf16_f32 v80, v80, s0
	v_cvt_pk_bf16_f32 v64, v64, s0
	v_cvt_pk_bf16_f32 v48, v48, s0
	v_cvt_pk_bf16_f32 v32, v32, s0
	v_cvt_pk_bf16_f32 v16, v16, s0
	ds_write_b16 v128, v0 offset:13888
	v_cvt_pk_bf16_f32 v0, v1, s0
	ds_write_b16 v128, v112
	v_cvt_pk_bf16_f32 v112, v113, s0
	ds_write_b16 v128, v96 offset:64
	v_cvt_pk_bf16_f32 v96, v97, s0
	ds_write_b16 v128, v80 offset:4608
	v_cvt_pk_bf16_f32 v80, v81, s0
	ds_write_b16 v128, v64 offset:4672
	v_cvt_pk_bf16_f32 v64, v65, s0
	ds_write_b16 v128, v48 offset:9216
	v_cvt_pk_bf16_f32 v48, v49, s0
	ds_write_b16 v128, v32 offset:9280
	v_cvt_pk_bf16_f32 v32, v33, s0
	ds_write_b16 v128, v16 offset:13824
	v_cvt_pk_bf16_f32 v16, v17, s0
	ds_write_b16 v128, v0 offset:14032
	v_cvt_pk_bf16_f32 v0, v2, s0
	ds_write_b16 v128, v112 offset:144
	v_cvt_pk_bf16_f32 v112, v114, s0
	ds_write_b16 v128, v96 offset:208
	v_cvt_pk_bf16_f32 v96, v98, s0
	ds_write_b16 v128, v80 offset:4752
	v_cvt_pk_bf16_f32 v80, v82, s0
	ds_write_b16 v128, v64 offset:4816
	v_cvt_pk_bf16_f32 v64, v66, s0
	ds_write_b16 v128, v48 offset:9360
	v_cvt_pk_bf16_f32 v48, v50, s0
	ds_write_b16 v128, v32 offset:9424
	v_cvt_pk_bf16_f32 v32, v34, s0
	ds_write_b16 v128, v16 offset:13968
	v_cvt_pk_bf16_f32 v16, v18, s0
	ds_write_b16 v128, v0 offset:14176
	v_cvt_pk_bf16_f32 v0, v3, s0
	ds_write_b16 v128, v112 offset:288
	v_cvt_pk_bf16_f32 v112, v115, s0
	ds_write_b16 v128, v96 offset:352
	v_cvt_pk_bf16_f32 v96, v99, s0
	ds_write_b16 v128, v80 offset:4896
	v_cvt_pk_bf16_f32 v80, v83, s0
	ds_write_b16 v128, v64 offset:4960
	v_cvt_pk_bf16_f32 v64, v67, s0
	ds_write_b16 v128, v48 offset:9504
	v_cvt_pk_bf16_f32 v48, v51, s0
	ds_write_b16 v128, v32 offset:9568
	v_cvt_pk_bf16_f32 v32, v35, s0
	ds_write_b16 v128, v16 offset:14112
	v_cvt_pk_bf16_f32 v16, v19, s0
	ds_write_b16 v128, v0 offset:14320
	v_cvt_pk_bf16_f32 v0, v4, s0
	ds_write_b16 v128, v112 offset:432
	v_cvt_pk_bf16_f32 v112, v116, s0
	ds_write_b16 v128, v96 offset:496
	v_cvt_pk_bf16_f32 v96, v100, s0
	ds_write_b16 v128, v80 offset:5040
	v_cvt_pk_bf16_f32 v80, v84, s0
	ds_write_b16 v128, v64 offset:5104
	v_cvt_pk_bf16_f32 v64, v68, s0
	ds_write_b16 v128, v48 offset:9648
	v_cvt_pk_bf16_f32 v48, v52, s0
	ds_write_b16 v128, v32 offset:9712
	v_cvt_pk_bf16_f32 v32, v36, s0
	ds_write_b16 v128, v16 offset:14256
	v_cvt_pk_bf16_f32 v16, v20, s0
	ds_write_b16 v128, v0 offset:15040
	v_cvt_pk_bf16_f32 v0, v5, s0
	ds_write_b16 v128, v112 offset:1152
	v_cvt_pk_bf16_f32 v112, v117, s0
	ds_write_b16 v128, v96 offset:1216
	v_cvt_pk_bf16_f32 v96, v101, s0
	ds_write_b16 v128, v80 offset:5760
	v_cvt_pk_bf16_f32 v80, v85, s0
	ds_write_b16 v128, v64 offset:5824
	v_cvt_pk_bf16_f32 v64, v69, s0
	ds_write_b16 v128, v48 offset:10368
	v_cvt_pk_bf16_f32 v48, v53, s0
	ds_write_b16 v128, v32 offset:10432
	v_cvt_pk_bf16_f32 v32, v37, s0
	ds_write_b16 v128, v16 offset:14976
	v_cvt_pk_bf16_f32 v16, v21, s0
	ds_write_b16 v128, v0 offset:15184
	v_cvt_pk_bf16_f32 v0, v6, s0
	ds_write_b16 v128, v112 offset:1296
	v_cvt_pk_bf16_f32 v112, v118, s0
	ds_write_b16 v128, v96 offset:1360
	v_cvt_pk_bf16_f32 v96, v102, s0
	ds_write_b16 v128, v80 offset:5904
	v_cvt_pk_bf16_f32 v80, v86, s0
	ds_write_b16 v128, v64 offset:5968
	v_cvt_pk_bf16_f32 v64, v70, s0
	ds_write_b16 v128, v48 offset:10512
	v_cvt_pk_bf16_f32 v48, v54, s0
	ds_write_b16 v128, v32 offset:10576
	v_cvt_pk_bf16_f32 v32, v38, s0
	ds_write_b16 v128, v16 offset:15120
	v_cvt_pk_bf16_f32 v16, v22, s0
; __device__ __forceinline__ int accrow(int reg, int lh) { return (reg & 3) + 8 * (reg >> 2) + 4 * lh; }
; template <int EPI, int PN>
; __device__ void gemm_phase(const Params& p, const u16* __restrict__ A, const u16* __restrict__ Bt, int nNt, char* smem) {
;     ...
; #pragma unroll
;       for (int i = 0; i < 4; ++i)
; #pragma unroll
;         for (int j = 0; j < 2; ++j)
; #pragma unroll
;           for (int r = 0; r < 16; ++r) *(u16*)(et + (i * 32 + accrow(r, lhE)) * 144 + (j * 32 + lrE) * 2) = f2bf(acc[i][j][r]);
; #pragma unroll
;       for (int it = 0; it < 16; ++it) {
;         const int c = it * 64 + laneE, row = c >> 3, seg = c & 7;
;         const uint4 v = *(const uint4*)(et + row * 144 + seg * 16);
;         if (EPI == 0) *(uint4*)(p.proj + (row0 + row) * NPROJ + col0 + seg * 8) = v;
;         else *(uint4*)(p.qp + (row0 + row) * DM + col0 + seg * 8) = v;
	ds_write_b16 v128, v0 offset:15328
	v_cvt_pk_bf16_f32 v0, v7, s0
	ds_write_b16 v128, v112 offset:1440
	v_cvt_pk_bf16_f32 v112, v119, s0
	ds_write_b16 v128, v96 offset:1504
	v_cvt_pk_bf16_f32 v96, v103, s0
	ds_write_b16 v128, v80 offset:6048
	v_cvt_pk_bf16_f32 v80, v87, s0
	ds_write_b16 v128, v64 offset:6112
	v_cvt_pk_bf16_f32 v64, v71, s0
	ds_write_b16 v128, v48 offset:10656
	v_cvt_pk_bf16_f32 v48, v55, s0
	ds_write_b16 v128, v32 offset:10720
	v_cvt_pk_bf16_f32 v32, v39, s0
	ds_write_b16 v128, v16 offset:15264
	v_cvt_pk_bf16_f32 v16, v23, s0
	ds_write_b16 v128, v0 offset:15472
	v_cvt_pk_bf16_f32 v0, v8, s0
	ds_write_b16 v128, v112 offset:1584
	v_cvt_pk_bf16_f32 v112, v120, s0
	ds_write_b16 v128, v96 offset:1648
	v_cvt_pk_bf16_f32 v96, v104, s0
	ds_write_b16 v128, v80 offset:6192
	v_cvt_pk_bf16_f32 v80, v88, s0
	ds_write_b16 v128, v64 offset:6256
	v_cvt_pk_bf16_f32 v64, v72, s0
	ds_write_b16 v128, v48 offset:10800
	v_cvt_pk_bf16_f32 v48, v56, s0
	ds_write_b16 v128, v32 offset:10864
	v_cvt_pk_bf16_f32 v32, v40, s0
	ds_write_b16 v128, v16 offset:15408
	v_cvt_pk_bf16_f32 v16, v24, s0
	ds_write_b16 v128, v0 offset:16192
	v_cvt_pk_bf16_f32 v0, v9, s0
	ds_write_b16 v128, v112 offset:2304
	v_cvt_pk_bf16_f32 v112, v121, s0
	ds_write_b16 v128, v96 offset:2368
	v_cvt_pk_bf16_f32 v96, v105, s0
	ds_write_b16 v128, v80 offset:6912
	v_cvt_pk_bf16_f32 v80, v89, s0
	ds_write_b16 v128, v64 offset:6976
	v_cvt_pk_bf16_f32 v64, v73, s0
	ds_write_b16 v128, v48 offset:11520
	v_cvt_pk_bf16_f32 v48, v57, s0
	ds_write_b16 v128, v32 offset:11584
	v_cvt_pk_bf16_f32 v32, v41, s0
	ds_write_b16 v128, v16 offset:16128
	v_cvt_pk_bf16_f32 v16, v25, s0
	ds_write_b16 v128, v0 offset:16336
	v_cvt_pk_bf16_f32 v0, v10, s0
	ds_write_b16 v128, v112 offset:2448
	v_cvt_pk_bf16_f32 v112, v122, s0
	ds_write_b16 v128, v96 offset:2512
	v_cvt_pk_bf16_f32 v96, v106, s0
	ds_write_b16 v128, v80 offset:7056
	v_cvt_pk_bf16_f32 v80, v90, s0
	ds_write_b16 v128, v64 offset:7120
	v_cvt_pk_bf16_f32 v64, v74, s0
	ds_write_b16 v128, v48 offset:11664
	v_cvt_pk_bf16_f32 v48, v58, s0
	ds_write_b16 v128, v32 offset:11728
	v_cvt_pk_bf16_f32 v32, v42, s0
	ds_write_b16 v128, v16 offset:16272
	v_cvt_pk_bf16_f32 v16, v26, s0
	ds_write_b16 v128, v0 offset:16480
	v_cvt_pk_bf16_f32 v0, v11, s0
	ds_write_b16 v128, v112 offset:2592
	v_cvt_pk_bf16_f32 v112, v123, s0
	ds_write_b16 v128, v96 offset:2656
	v_cvt_pk_bf16_f32 v96, v107, s0
	ds_write_b16 v128, v80 offset:7200
	v_cvt_pk_bf16_f32 v80, v91, s0
	ds_write_b16 v128, v64 offset:7264
	v_cvt_pk_bf16_f32 v64, v75, s0
	ds_write_b16 v128, v48 offset:11808
	v_cvt_pk_bf16_f32 v48, v59, s0
	ds_write_b16 v128, v32 offset:11872
	v_cvt_pk_bf16_f32 v32, v43, s0
	ds_write_b16 v128, v16 offset:16416
	v_cvt_pk_bf16_f32 v16, v27, s0
	ds_write_b16 v128, v0 offset:16624
	v_cvt_pk_bf16_f32 v0, v12, s0
	ds_write_b16 v128, v112 offset:2736
	v_cvt_pk_bf16_f32 v112, v124, s0
	ds_write_b16 v128, v96 offset:2800
	v_cvt_pk_bf16_f32 v96, v108, s0
	ds_write_b16 v128, v80 offset:7344
	v_cvt_pk_bf16_f32 v80, v92, s0
	ds_write_b16 v128, v64 offset:7408
	v_cvt_pk_bf16_f32 v64, v76, s0
	ds_write_b16 v128, v48 offset:11952
	v_cvt_pk_bf16_f32 v48, v60, s0
	ds_write_b16 v128, v32 offset:12016
	v_cvt_pk_bf16_f32 v32, v44, s0
	ds_write_b16 v128, v16 offset:16560
	v_cvt_pk_bf16_f32 v16, v28, s0
	ds_write_b16 v128, v0 offset:17344
	v_cvt_pk_bf16_f32 v0, v13, s0
	ds_write_b16 v128, v112 offset:3456
	v_cvt_pk_bf16_f32 v112, v125, s0
	ds_write_b16 v128, v96 offset:3520
	v_cvt_pk_bf16_f32 v96, v109, s0
	ds_write_b16 v128, v80 offset:8064
	v_cvt_pk_bf16_f32 v80, v93, s0
	ds_write_b16 v128, v64 offset:8128
	v_cvt_pk_bf16_f32 v64, v77, s0
	ds_write_b16 v128, v48 offset:12672
	v_cvt_pk_bf16_f32 v48, v61, s0
	ds_write_b16 v128, v32 offset:12736
	v_cvt_pk_bf16_f32 v32, v45, s0
	ds_write_b16 v128, v16 offset:17280
	v_cvt_pk_bf16_f32 v16, v29, s0
	ds_write_b16 v128, v0 offset:17488
	v_cvt_pk_bf16_f32 v0, v14, s0
	ds_write_b16 v128, v112 offset:3600
	v_cvt_pk_bf16_f32 v112, v126, s0
	ds_write_b16 v128, v96 offset:3664
	v_cvt_pk_bf16_f32 v96, v110, s0
	ds_write_b16 v128, v80 offset:8208
	v_cvt_pk_bf16_f32 v80, v94, s0
	ds_write_b16 v128, v64 offset:8272
	v_cvt_pk_bf16_f32 v64, v78, s0
	ds_write_b16 v128, v48 offset:12816
	v_cvt_pk_bf16_f32 v48, v62, s0
	ds_write_b16 v128, v32 offset:12880
	v_cvt_pk_bf16_f32 v32, v46, s0
	ds_write_b16 v128, v16 offset:17424
	v_cvt_pk_bf16_f32 v16, v30, s0
	ds_write_b16 v128, v0 offset:17632
	v_cvt_pk_bf16_f32 v0, v15, s0
	s_ashr_i32 s11, s10, 31
	ds_write_b16 v128, v112 offset:3744
	v_cvt_pk_bf16_f32 v112, v127, s0
	ds_write_b16 v128, v96 offset:3808
	v_cvt_pk_bf16_f32 v96, v111, s0
	ds_write_b16 v128, v80 offset:8352
	v_cvt_pk_bf16_f32 v80, v95, s0
	ds_write_b16 v128, v64 offset:8416
	v_cvt_pk_bf16_f32 v64, v79, s0
	ds_write_b16 v128, v48 offset:12960
	v_cvt_pk_bf16_f32 v48, v63, s0
	ds_write_b16 v128, v32 offset:13024
	v_cvt_pk_bf16_f32 v32, v47, s0
	ds_write_b16 v128, v16 offset:17568
	v_cvt_pk_bf16_f32 v16, v31, s0
	ds_write_b16 v128, v0 offset:17776
	v_lshlrev_b32_e32 v0, 4, v149
	s_lshl_b64 s[10:11], s[10:11], 8
	ds_write_b16 v128, v112 offset:3888
	ds_write_b16 v128, v96 offset:3952
	ds_write_b16 v128, v80 offset:8496
	ds_write_b16 v128, v64 offset:8560
	ds_write_b16 v128, v48 offset:13104
	ds_write_b16 v128, v32 offset:13168
	ds_write_b16 v128, v16 offset:17712
	v_and_b32_e32 v128, 0x70, v0
	v_ashrrev_i32_e32 v6, 3, v149
	v_mov_b32_e32 v9, s11
	v_or_b32_e32 v8, s10, v134
	v_add_u32_e32 v10, v163, v128
	v_ashrrev_i32_e32 v7, 31, v6
	v_lshl_add_u32 v4, s14, 8, v145
	v_mad_u64_u32 v[0:1], s[10:11], v6, s13, v[10:11]
	v_lshl_add_u64 v[6:7], v[8:9], 0, v[6:7]
	v_readlane_b32 s16, v253, 39
	v_ashrrev_i32_e32 v5, 31, v4
	v_lshlrev_b64 v[6:7], 12, v[6:7]
	v_readlane_b32 s26, v253, 49
	v_readlane_b32 s27, v253, 50
	ds_read_b128 v[0:3], v0
	v_lshlrev_b64 v[12:13], 1, v[4:5]
	v_lshl_add_u64 v[6:7], s[26:27], 0, v[6:7]
	v_lshl_add_u64 v[4:5], v[6:7], 0, v[12:13]
	v_lshl_add_u64 v[14:15], v[4:5], 0, v[128:129]
	v_add_u32_e32 v4, 64, v149
	v_ashrrev_i32_e32 v16, 3, v4
	v_mad_u64_u32 v[4:5], s[10:11], v16, s13, v[10:11]
	v_ashrrev_i32_e32 v17, 31, v16
	ds_read_b128 v[4:7], v4
	s_waitcnt lgkmcnt(1)
; template <int EPI, int PN>
; __device__ void gemm_phase(const Params& p, const u16* __restrict__ A, const u16* __restrict__ Bt, int nNt, char* smem) {
;     ...
;       for (int it = 0; it < 16; ++it) {
;         const int c = it * 64 + laneE, row = c >> 3, seg = c & 7;
;         const uint4 v = *(const uint4*)(et + row * 144 + seg * 16);
;         if (EPI == 0) *(uint4*)(p.proj + (row0 + row) * NPROJ + col0 + seg * 8) = v;
;         else *(uint4*)(p.qp + (row0 + row) * DM + col0 + seg * 8) = v;
;       }
	global_store_dwordx4 v[14:15], v[0:3], off
	v_readlane_b32 s17, v253, 40
	v_readlane_b32 s18, v253, 41
	v_lshl_add_u64 v[0:1], v[8:9], 0, v[16:17]
	v_lshlrev_b64 v[0:1], 12, v[0:1]
	v_lshl_add_u64 v[0:1], s[26:27], 0, v[0:1]
	v_lshl_add_u64 v[0:1], v[0:1], 0, v[12:13]
	v_lshl_add_u64 v[0:1], v[0:1], 0, v[128:129]
	s_waitcnt lgkmcnt(0)
	global_store_dwordx4 v[0:1], v[4:7], off
	v_add_u32_e32 v0, 0x80, v149
	v_readlane_b32 s19, v253, 42
	v_ashrrev_i32_e32 v4, 3, v0
	v_ashrrev_i32_e32 v5, 31, v4
	v_mad_u64_u32 v[0:1], s[10:11], v4, s13, v[10:11]
	v_lshl_add_u64 v[4:5], v[8:9], 0, v[4:5]
	v_lshlrev_b64 v[4:5], 12, v[4:5]
	ds_read_b128 v[0:3], v0
	v_lshl_add_u64 v[4:5], s[26:27], 0, v[4:5]
	v_lshl_add_u64 v[4:5], v[4:5], 0, v[12:13]
	v_lshl_add_u64 v[14:15], v[4:5], 0, v[128:129]
	v_add_u32_e32 v4, 0xc0, v149
	v_ashrrev_i32_e32 v16, 3, v4
	v_mad_u64_u32 v[4:5], s[10:11], v16, s13, v[10:11]
	v_ashrrev_i32_e32 v17, 31, v16
	ds_read_b128 v[4:7], v4
	s_waitcnt lgkmcnt(1)
	global_store_dwordx4 v[14:15], v[0:3], off
	v_readlane_b32 s20, v253, 43
	v_readlane_b32 s21, v253, 44
	v_lshl_add_u64 v[0:1], v[8:9], 0, v[16:17]
	v_lshlrev_b64 v[0:1], 12, v[0:1]
	v_lshl_add_u64 v[0:1], s[26:27], 0, v[0:1]
	v_lshl_add_u64 v[0:1], v[0:1], 0, v[12:13]
	v_lshl_add_u64 v[0:1], v[0:1], 0, v[128:129]
	s_waitcnt lgkmcnt(0)
	global_store_dwordx4 v[0:1], v[4:7], off
	v_add_u32_e32 v0, 0x100, v149
	v_readlane_b32 s22, v253, 45
	v_ashrrev_i32_e32 v4, 3, v0
	v_ashrrev_i32_e32 v5, 31, v4
	v_mad_u64_u32 v[0:1], s[10:11], v4, s13, v[10:11]
	v_lshl_add_u64 v[4:5], v[8:9], 0, v[4:5]
	v_lshlrev_b64 v[4:5], 12, v[4:5]
	ds_read_b128 v[0:3], v0
	v_lshl_add_u64 v[4:5], s[26:27], 0, v[4:5]
	v_lshl_add_u64 v[4:5], v[4:5], 0, v[12:13]
	v_lshl_add_u64 v[14:15], v[4:5], 0, v[128:129]
	v_add_u32_e32 v4, 0x140, v149
	v_ashrrev_i32_e32 v16, 3, v4
	v_mad_u64_u32 v[4:5], s[10:11], v16, s13, v[10:11]
	v_ashrrev_i32_e32 v17, 31, v16
	ds_read_b128 v[4:7], v4
	s_waitcnt lgkmcnt(1)
	global_store_dwordx4 v[14:15], v[0:3], off
	v_readlane_b32 s23, v253, 46
	v_readlane_b32 s24, v253, 47
	v_lshl_add_u64 v[0:1], v[8:9], 0, v[16:17]
	v_lshlrev_b64 v[0:1], 12, v[0:1]
	v_lshl_add_u64 v[0:1], s[26:27], 0, v[0:1]
	v_lshl_add_u64 v[0:1], v[0:1], 0, v[12:13]
	v_lshl_add_u64 v[0:1], v[0:1], 0, v[128:129]
	s_waitcnt lgkmcnt(0)
	global_store_dwordx4 v[0:1], v[4:7], off
	v_add_u32_e32 v0, 0x180, v149
	v_readlane_b32 s25, v253, 48
	v_ashrrev_i32_e32 v4, 3, v0
	v_ashrrev_i32_e32 v5, 31, v4
	v_mad_u64_u32 v[0:1], s[10:11], v4, s13, v[10:11]
	v_lshl_add_u64 v[4:5], v[8:9], 0, v[4:5]
	v_lshlrev_b64 v[4:5], 12, v[4:5]
	ds_read_b128 v[0:3], v0
	v_lshl_add_u64 v[4:5], s[26:27], 0, v[4:5]
	v_lshl_add_u64 v[4:5], v[4:5], 0, v[12:13]
	v_lshl_add_u64 v[14:15], v[4:5], 0, v[128:129]
	v_add_u32_e32 v4, 0x1c0, v149
	v_ashrrev_i32_e32 v16, 3, v4
	v_mad_u64_u32 v[4:5], s[10:11], v16, s13, v[10:11]
	v_ashrrev_i32_e32 v17, 31, v16
	ds_read_b128 v[4:7], v4
	s_waitcnt lgkmcnt(1)
	global_store_dwordx4 v[14:15], v[0:3], off
	v_readlane_b32 s28, v253, 51
	v_readlane_b32 s29, v253, 52
	v_lshl_add_u64 v[0:1], v[8:9], 0, v[16:17]
	v_lshlrev_b64 v[0:1], 12, v[0:1]
	v_lshl_add_u64 v[0:1], s[26:27], 0, v[0:1]
	v_lshl_add_u64 v[0:1], v[0:1], 0, v[12:13]
	v_lshl_add_u64 v[0:1], v[0:1], 0, v[128:129]
	s_waitcnt lgkmcnt(0)
	global_store_dwordx4 v[0:1], v[4:7], off
	v_add_u32_e32 v0, 0x200, v149
	v_readlane_b32 s30, v253, 53
	v_ashrrev_i32_e32 v4, 3, v0
	v_ashrrev_i32_e32 v5, 31, v4
	v_mad_u64_u32 v[0:1], s[10:11], v4, s13, v[10:11]
	v_lshl_add_u64 v[4:5], v[8:9], 0, v[4:5]
	v_lshlrev_b64 v[4:5], 12, v[4:5]
	ds_read_b128 v[0:3], v0
	v_lshl_add_u64 v[4:5], s[26:27], 0, v[4:5]
	v_lshl_add_u64 v[4:5], v[4:5], 0, v[12:13]
	v_lshl_add_u64 v[14:15], v[4:5], 0, v[128:129]
	v_add_u32_e32 v4, 0x240, v149
	v_ashrrev_i32_e32 v16, 3, v4
	v_mad_u64_u32 v[4:5], s[10:11], v16, s13, v[10:11]
	v_ashrrev_i32_e32 v17, 31, v16
	ds_read_b128 v[4:7], v4
	s_waitcnt lgkmcnt(1)
; template <int EPI, int PN>
; __device__ void gemm_phase(const Params& p, const u16* __restrict__ A, const u16* __restrict__ Bt, int nNt, char* smem) {
;     ...
;   for (int q = jb;; q += NJ) {
;     const int pl = q / (4 * PN), w = q % (4 * PN);
;     const int gp = pl * 8 + xcd;
;     if (gp >= npatch) break;
;     ...
;       for (int it = 0; it < 16; ++it) {
;         const int c = it * 64 + laneE, row = c >> 3, seg = c & 7;
;         const uint4 v = *(const uint4*)(et + row * 144 + seg * 16);
;         if (EPI == 0) *(uint4*)(p.proj + (row0 + row) * NPROJ + col0 + seg * 8) = v;
;         else *(uint4*)(p.qp + (row0 + row) * DM + col0 + seg * 8) = v;
;       }
;     }
;     __syncthreads();
	global_store_dwordx4 v[14:15], v[0:3], off
	v_readlane_b32 s31, v253, 54
	s_nop 0
	v_lshl_add_u64 v[0:1], v[8:9], 0, v[16:17]
	v_lshlrev_b64 v[0:1], 12, v[0:1]
	v_lshl_add_u64 v[0:1], s[26:27], 0, v[0:1]
	v_lshl_add_u64 v[0:1], v[0:1], 0, v[12:13]
	v_lshl_add_u64 v[0:1], v[0:1], 0, v[128:129]
	s_waitcnt lgkmcnt(0)
	global_store_dwordx4 v[0:1], v[4:7], off
	v_add_u32_e32 v0, 0x280, v149
	s_nop 0
	v_ashrrev_i32_e32 v4, 3, v0
	v_ashrrev_i32_e32 v5, 31, v4
	v_mad_u64_u32 v[0:1], s[10:11], v4, s13, v[10:11]
	v_lshl_add_u64 v[4:5], v[8:9], 0, v[4:5]
	v_lshlrev_b64 v[4:5], 12, v[4:5]
	ds_read_b128 v[0:3], v0
	v_lshl_add_u64 v[4:5], s[26:27], 0, v[4:5]
	v_lshl_add_u64 v[4:5], v[4:5], 0, v[12:13]
	v_lshl_add_u64 v[14:15], v[4:5], 0, v[128:129]
	v_add_u32_e32 v4, 0x2c0, v149
	v_ashrrev_i32_e32 v16, 3, v4
	v_mad_u64_u32 v[4:5], s[10:11], v16, s13, v[10:11]
	v_ashrrev_i32_e32 v17, 31, v16
	ds_read_b128 v[4:7], v4
	s_waitcnt lgkmcnt(1)
	global_store_dwordx4 v[14:15], v[0:3], off
	s_nop 1
	v_lshl_add_u64 v[0:1], v[8:9], 0, v[16:17]
	v_lshlrev_b64 v[0:1], 12, v[0:1]
	v_lshl_add_u64 v[0:1], s[26:27], 0, v[0:1]
	v_lshl_add_u64 v[0:1], v[0:1], 0, v[12:13]
	v_lshl_add_u64 v[0:1], v[0:1], 0, v[128:129]
	s_waitcnt lgkmcnt(0)
	global_store_dwordx4 v[0:1], v[4:7], off
	v_add_u32_e32 v0, 0x300, v149
	s_nop 0
	v_ashrrev_i32_e32 v4, 3, v0
	v_ashrrev_i32_e32 v5, 31, v4
	v_mad_u64_u32 v[0:1], s[10:11], v4, s13, v[10:11]
	v_lshl_add_u64 v[4:5], v[8:9], 0, v[4:5]
	v_lshlrev_b64 v[4:5], 12, v[4:5]
	ds_read_b128 v[0:3], v0
	v_lshl_add_u64 v[4:5], s[26:27], 0, v[4:5]
	v_lshl_add_u64 v[4:5], v[4:5], 0, v[12:13]
	v_lshl_add_u64 v[14:15], v[4:5], 0, v[128:129]
	v_add_u32_e32 v4, 0x340, v149
	v_ashrrev_i32_e32 v16, 3, v4
	v_mad_u64_u32 v[4:5], s[10:11], v16, s13, v[10:11]
	v_ashrrev_i32_e32 v17, 31, v16
	ds_read_b128 v[4:7], v4
	s_waitcnt lgkmcnt(1)
	global_store_dwordx4 v[14:15], v[0:3], off
	s_nop 1
	v_lshl_add_u64 v[0:1], v[8:9], 0, v[16:17]
	v_lshlrev_b64 v[0:1], 12, v[0:1]
	v_lshl_add_u64 v[0:1], s[26:27], 0, v[0:1]
	v_lshl_add_u64 v[0:1], v[0:1], 0, v[12:13]
	v_lshl_add_u64 v[0:1], v[0:1], 0, v[128:129]
	s_waitcnt lgkmcnt(0)
	global_store_dwordx4 v[0:1], v[4:7], off
	v_add_u32_e32 v0, 0x380, v149
	s_nop 0
	v_ashrrev_i32_e32 v4, 3, v0
	v_ashrrev_i32_e32 v5, 31, v4
	v_mad_u64_u32 v[0:1], s[10:11], v4, s13, v[10:11]
	v_lshl_add_u64 v[4:5], v[8:9], 0, v[4:5]
	v_lshlrev_b64 v[4:5], 12, v[4:5]
	v_lshl_add_u64 v[4:5], s[26:27], 0, v[4:5]
	v_lshl_add_u64 v[4:5], v[4:5], 0, v[12:13]
	v_lshl_add_u64 v[14:15], v[4:5], 0, v[128:129]
	v_add_u32_e32 v4, 0x3c0, v149
	v_ashrrev_i32_e32 v16, 3, v4
	ds_read_b128 v[0:3], v0
	v_mad_u64_u32 v[4:5], s[10:11], v16, s13, v[10:11]
	v_readlane_b32 s10, v254, 28
	s_add_i32 s34, s34, s10
	s_ashr_i32 s10, s34, 31
	v_ashrrev_i32_e32 v17, 31, v16
	s_lshr_b32 s10, s10, 27
	ds_read_b128 v[4:7], v4
	s_waitcnt lgkmcnt(1)
	global_store_dwordx4 v[14:15], v[0:3], off
	s_add_i32 s10, s34, s10
	s_ashr_i32 s10, s10, 5
	v_lshl_add_u64 v[0:1], v[8:9], 0, v[16:17]
	v_lshlrev_b64 v[0:1], 12, v[0:1]
	v_lshl_add_u64 v[0:1], s[26:27], 0, v[0:1]
	s_lshl_b32 s10, s10, 3
	v_readlane_b32 s11, v254, 24
	v_lshl_add_u64 v[0:1], v[0:1], 0, v[12:13]
	s_or_b32 s11, s10, s11
	v_lshl_add_u64 v[0:1], v[0:1], 0, v[128:129]
	s_cmp_gt_i32 s11, 31
	s_waitcnt lgkmcnt(0)
	global_store_dwordx4 v[0:1], v[4:7], off
	s_waitcnt vmcnt(63) expcnt(7) lgkmcnt(15)
	s_barrier
	s_cbranch_scc0 .LBB0_722
